# phase 6: MergeFin second-half tile loads requested with the first half; MergeMid tile loads left in flight across the stage-release barriers; phase 7: final_norm_w loads requested before the ssq wait
# speedup vs baseline: 1.0007x; 1.0002x over previous
; #define PG8_STAGE(bufoff, gbase, voff) do { _Pragma("unroll") for (int _i = 0; _i < 2; ++_i) \
;         __builtin_amdgcn_global_load_lds((const unsigned*)((const char*)(gbase) + (voff)[_i]), (LAS unsigned*)(lds + (bufoff) + ldsw + _i * 8192), 16, 0, 0); } while (0)
; #define PG8_LDA(dst, b, h) do { _Pragma("unroll") for (int m = 0; m < 4; ++m) _Pragma("unroll") for (int k = 0; k < 2; ++k) dst[m][k] = *(const LAS bf16x8*)(lds + PG8_SA(b, h) + aoff + m * 2048 + k * 1024); } while (0)
; #define PG8_LDB(dst, b, h) do { _Pragma("unroll") for (int n = 0; n < 2; ++n) _Pragma("unroll") for (int k = 0; k < 2; ++k) dst[n][k] = *(const LAS bf16x8*)(lds + PG8_SB(b, h) + boff + n * 2048 + k * 1024); } while (0)
; #define PG8_MMA(ai, bj, At, Bt) do { __builtin_amdgcn_s_setprio(1); _Pragma("unroll") for (int m = 0; m < 4; ++m) _Pragma("unroll") for (int n = 0; n < 2; ++n) _Pragma("unroll") for (int k = 0; k < 2; ++k) \
;         acc[ai][bj][m][n] = __builtin_amdgcn_mfma_f32_16x16x32_bf16(Bt[n][k], At[m][k], acc[ai][bj][m][n], 0, 0, 0); __builtin_amdgcn_s_setprio(0); } while (0)
; #define PG8_WAIT_L(n) asm volatile("s_waitcnt lgkmcnt(" #n ")" ::: "memory")
; #define PG8_BAR __builtin_amdgcn_s_barrier()
; #define PG8_SCHED __builtin_amdgcn_sched_barrier(0)
; template <class Epi, class Sched, bool ZERO>
; __device__ __forceinline__ void gemm_phase_acc(LAS unsigned char* lds, const Gemm g, const Sched& S, const Epi& E, f32x4 (&acc)[2][2][4][2]) {
;     ...
;             PG8_LDB(B0, 0, 0); PG8_SCHED; PG8_LDA(At, 0, 0); PG8_STAGE(PG8_SA(1, 1), a1 + hstep, voffA);
;             PG8_WAIT_L(8); PG8_BAR; PG8_WAIT_L(0); PG8_MMA(0, 0, At, B0); PG8_BAR; PG8_SCHED;
;             PG8_LDB(B1, 0, 1); PG8_STAGE(PG8_SB(0, 0), b2, voffB);
;             PG8_BAR; PG8_WAIT_L(0); PG8_MMA(0, 1, At, B1); PG8_BAR;
;             PG8_LDA(At, 0, 1); PG8_STAGE(PG8_SA(0, 0), a2, voffA);
;             PG8_BAR; PG8_WAIT_L(0); PG8_MMA(1, 0, At, B0); PG8_BAR; PG8_SCHED;
.LBB0_973:
	s_add_u32 s10, s6, s8
	ds_read_b128 v[146:149], v141
	ds_read_b128 v[150:153], v141 offset:1024
	ds_read_b128 v[154:157], v141 offset:2048
	ds_read_b128 v[158:161], v141 offset:3072
	s_addc_u32 s11, s7, s9
	s_add_u32 s10, s10, 0x9400100
	s_addc_u32 s11, s11, 0
	s_add_u32 s50, s31, s8
	s_addc_u32 s51, s38, s9
	s_cmpk_eq_i32 s8, 0x300
	s_cselect_b32 s15, s3, s11
	s_cselect_b32 s14, s2, s10
	s_cselect_b32 s11, s1, s51
	s_cselect_b32 s10, s0, s50
	s_mov_b32 m0, s40
	v_lshl_add_u64 v[194:195], v[136:137], 0, s[8:9]
	ds_read_b128 v[162:165], v142
	ds_read_b128 v[166:169], v142 offset:1024
	ds_read_b128 v[170:173], v142 offset:2048
	ds_read_b128 v[174:177], v142 offset:3072
	ds_read_b128 v[178:181], v142 offset:4096
	ds_read_b128 v[182:185], v142 offset:5120
	ds_read_b128 v[186:189], v142 offset:6144
	ds_read_b128 v[190:193], v142 offset:7168
	global_load_lds_dwordx4 v[194:195], off
	v_lshl_add_u64 v[194:195], v[138:139], 0, s[8:9]
	s_mov_b32 m0, s41
	s_nop 0
	global_load_lds_dwordx4 v[194:195], off
	s_waitcnt lgkmcnt(8)
	s_barrier
	s_waitcnt lgkmcnt(0)
	s_setprio 1
	s_waitcnt lgkmcnt(0)
	v_mfma_f32_16x16x32_bf16 v[104:107], v[146:149], v[162:165], v[104:107]
	v_mfma_f32_16x16x32_bf16 v[108:111], v[154:157], v[162:165], v[108:111]
	v_mfma_f32_16x16x32_bf16 v[124:127], v[146:149], v[170:173], v[124:127]
	v_mfma_f32_16x16x32_bf16 v[116:119], v[154:157], v[170:173], v[116:119]
	v_mfma_f32_16x16x32_bf16 v[96:99], v[146:149], v[178:181], v[96:99]
	v_mfma_f32_16x16x32_bf16 v[88:91], v[154:157], v[178:181], v[88:91]
	v_mfma_f32_16x16x32_bf16 v[80:83], v[146:149], v[186:189], v[80:83]
	v_mfma_f32_16x16x32_bf16 v[72:75], v[154:157], v[186:189], v[72:75]
	v_mfma_f32_16x16x32_bf16 v[104:107], v[150:153], v[166:169], v[104:107]
	v_mfma_f32_16x16x32_bf16 v[108:111], v[158:161], v[166:169], v[108:111]
	v_mfma_f32_16x16x32_bf16 v[124:127], v[150:153], v[174:177], v[124:127]
	v_mfma_f32_16x16x32_bf16 v[116:119], v[158:161], v[174:177], v[116:119]
	v_mfma_f32_16x16x32_bf16 v[96:99], v[150:153], v[182:185], v[96:99]
	v_mfma_f32_16x16x32_bf16 v[88:91], v[158:161], v[182:185], v[88:91]
	v_mfma_f32_16x16x32_bf16 v[80:83], v[150:153], v[190:193], v[80:83]
	v_mfma_f32_16x16x32_bf16 v[72:75], v[158:161], v[190:193], v[72:75]
	s_setprio 0
	s_barrier
	s_mov_b32 m0, s42
	v_lshl_add_u64 v[210:211], s[10:11], 0, v[132:133]
	ds_read_b128 v[194:197], v143
	ds_read_b128 v[198:201], v143 offset:1024
	ds_read_b128 v[202:205], v143 offset:2048
	ds_read_b128 v[206:209], v143 offset:3072
	global_load_lds_dwordx4 v[210:211], off
	v_lshl_add_u64 v[212:213], s[10:11], 0, v[128:129]
	s_mov_b32 m0, s43
	s_nop 0
	global_load_lds_dwordx4 v[212:213], off
	s_barrier
	s_waitcnt lgkmcnt(0)
	s_setprio 1
	s_waitcnt lgkmcnt(0)
	v_mfma_f32_16x16x32_bf16 v[112:115], v[194:197], v[162:165], v[112:115]
	v_mfma_f32_16x16x32_bf16 v[120:123], v[202:205], v[162:165], v[120:123]
	v_mfma_f32_16x16x32_bf16 v[100:103], v[194:197], v[170:173], v[100:103]
	v_mfma_f32_16x16x32_bf16 v[92:95], v[202:205], v[170:173], v[92:95]
	v_mfma_f32_16x16x32_bf16 v[84:87], v[194:197], v[178:181], v[84:87]
	v_mfma_f32_16x16x32_bf16 v[76:79], v[202:205], v[178:181], v[76:79]
	v_mfma_f32_16x16x32_bf16 v[68:71], v[194:197], v[186:189], v[68:71]
	v_mfma_f32_16x16x32_bf16 v[56:59], v[202:205], v[186:189], v[56:59]
	v_mfma_f32_16x16x32_bf16 v[112:115], v[198:201], v[166:169], v[112:115]
	v_mfma_f32_16x16x32_bf16 v[120:123], v[206:209], v[166:169], v[120:123]
	v_mfma_f32_16x16x32_bf16 v[100:103], v[198:201], v[174:177], v[100:103]
	v_mfma_f32_16x16x32_bf16 v[92:95], v[206:209], v[174:177], v[92:95]
	v_mfma_f32_16x16x32_bf16 v[84:87], v[198:201], v[182:185], v[84:87]
	v_mfma_f32_16x16x32_bf16 v[76:79], v[206:209], v[182:185], v[76:79]
	v_mfma_f32_16x16x32_bf16 v[68:71], v[198:201], v[190:193], v[68:71]
	v_mfma_f32_16x16x32_bf16 v[56:59], v[206:209], v[190:193], v[56:59]
	s_setprio 0
	s_mov_b32 m0, s19
	v_lshl_add_u64 v[214:215], s[14:15], 0, v[134:135]
	s_barrier
	ds_read_b128 v[162:165], v142 offset:16384
	ds_read_b128 v[166:169], v142 offset:17408
	ds_read_b128 v[170:173], v142 offset:18432
	ds_read_b128 v[174:177], v142 offset:19456
	ds_read_b128 v[178:181], v142 offset:20480
	ds_read_b128 v[182:185], v142 offset:21504
	ds_read_b128 v[186:189], v142 offset:22528
	ds_read_b128 v[190:193], v142 offset:23552
	global_load_lds_dwordx4 v[214:215], off
	v_lshl_add_u64 v[216:217], s[14:15], 0, v[130:131]
	s_mov_b32 m0, s24
	s_nop 0
	global_load_lds_dwordx4 v[216:217], off
	s_barrier
	s_waitcnt lgkmcnt(0)
	s_setprio 1
	s_waitcnt lgkmcnt(0)
	v_mfma_f32_16x16x32_bf16 v[52:55], v[146:149], v[162:165], v[52:55]
	v_mfma_f32_16x16x32_bf16 v[48:51], v[154:157], v[162:165], v[48:51]
	v_mfma_f32_16x16x32_bf16 v[36:39], v[146:149], v[170:173], v[36:39]
	v_mfma_f32_16x16x32_bf16 v[32:35], v[154:157], v[170:173], v[32:35]
	v_mfma_f32_16x16x32_bf16 v[28:31], v[146:149], v[178:181], v[28:31]
	v_mfma_f32_16x16x32_bf16 v[8:11], v[154:157], v[178:181], v[8:11]
	v_mfma_f32_16x16x32_bf16 v[4:7], v[146:149], v[186:189], v[4:7]
	v_mfma_f32_16x16x32_bf16 v[0:3], v[154:157], v[186:189], v[0:3]
	v_mfma_f32_16x16x32_bf16 v[52:55], v[150:153], v[166:169], v[52:55]
	v_mfma_f32_16x16x32_bf16 v[48:51], v[158:161], v[166:169], v[48:51]
	v_mfma_f32_16x16x32_bf16 v[36:39], v[150:153], v[174:177], v[36:39]
	v_mfma_f32_16x16x32_bf16 v[32:35], v[158:161], v[174:177], v[32:35]
	v_mfma_f32_16x16x32_bf16 v[28:31], v[150:153], v[182:185], v[28:31]
	v_mfma_f32_16x16x32_bf16 v[8:11], v[158:161], v[182:185], v[8:11]
	v_mfma_f32_16x16x32_bf16 v[4:7], v[150:153], v[190:193], v[4:7]
	v_mfma_f32_16x16x32_bf16 v[0:3], v[158:161], v[190:193], v[0:3]
	s_setprio 0
	s_barrier
; #define PG8_STAGE(bufoff, gbase, voff) do { _Pragma("unroll") for (int _i = 0; _i < 2; ++_i) \
;         __builtin_amdgcn_global_load_lds((const unsigned*)((const char*)(gbase) + (voff)[_i]), (LAS unsigned*)(lds + (bufoff) + ldsw + _i * 8192), 16, 0, 0); } while (0)
; #define PG8_LDA(dst, b, h) do { _Pragma("unroll") for (int m = 0; m < 4; ++m) _Pragma("unroll") for (int k = 0; k < 2; ++k) dst[m][k] = *(const LAS bf16x8*)(lds + PG8_SA(b, h) + aoff + m * 2048 + k * 1024); } while (0)
; #define PG8_LDB(dst, b, h) do { _Pragma("unroll") for (int n = 0; n < 2; ++n) _Pragma("unroll") for (int k = 0; k < 2; ++k) dst[n][k] = *(const LAS bf16x8*)(lds + PG8_SB(b, h) + boff + n * 2048 + k * 1024); } while (0)
; #define PG8_MMA(ai, bj, At, Bt) do { __builtin_amdgcn_s_setprio(1); _Pragma("unroll") for (int m = 0; m < 4; ++m) _Pragma("unroll") for (int n = 0; n < 2; ++n) _Pragma("unroll") for (int k = 0; k < 2; ++k) \
;         acc[ai][bj][m][n] = __builtin_amdgcn_mfma_f32_16x16x32_bf16(Bt[n][k], At[m][k], acc[ai][bj][m][n], 0, 0, 0); __builtin_amdgcn_s_setprio(0); } while (0)
; #define PG8_WAIT_V(n) asm volatile("s_waitcnt vmcnt(" #n ")" ::: "memory")
; #define PG8_WAIT_L(n) asm volatile("s_waitcnt lgkmcnt(" #n ")" ::: "memory")
; #define PG8_BAR __builtin_amdgcn_s_barrier()
; #define PG8_SCHED __builtin_amdgcn_sched_barrier(0)
; template <class Epi, class Sched, bool ZERO>
; __device__ __forceinline__ void gemm_phase_acc(LAS unsigned char* lds, const Gemm g, const Sched& S, const Epi& E, f32x4 (&acc)[2][2][4][2]) {
;     ...
;             PG8_STAGE(PG8_SB(0, 1), b2 + hstep, voffB);
;             PG8_WAIT_V(6); PG8_BAR; PG8_MMA(1, 1, At, B1); PG8_BAR;
;             PG8_LDB(B0, 1, 0); PG8_SCHED; PG8_LDA(At, 1, 0); PG8_STAGE(PG8_SA(0, 1), a2 + hstep, voffA);
;             PG8_WAIT_L(8); PG8_BAR; PG8_WAIT_L(0); PG8_MMA(0, 0, At, B0); PG8_BAR; PG8_SCHED;
;             PG8_LDB(B1, 1, 1); PG8_STAGE(PG8_SB(1, 0), b3, voffB);
;             PG8_BAR; PG8_WAIT_L(0); PG8_MMA(0, 1, At, B1); PG8_BAR;
	s_add_u32 s50, s10, 0x20000
	s_addc_u32 s51, s11, 0
	s_mov_b32 m0, s44
	v_lshl_add_u64 v[146:147], s[50:51], 0, v[132:133]
	global_load_lds_dwordx4 v[146:147], off
	v_lshl_add_u64 v[146:147], s[50:51], 0, v[128:129]
	s_mov_b32 m0, s45
	s_nop 0
	global_load_lds_dwordx4 v[146:147], off
	s_waitcnt vmcnt(6)
	s_barrier
	s_setprio 1
	v_mfma_f32_16x16x32_bf16 v[64:67], v[194:197], v[162:165], v[64:67]
	v_mfma_f32_16x16x32_bf16 v[60:63], v[202:205], v[162:165], v[60:63]
	v_mfma_f32_16x16x32_bf16 v[44:47], v[194:197], v[170:173], v[44:47]
	v_mfma_f32_16x16x32_bf16 v[40:43], v[202:205], v[170:173], v[40:43]
	v_mfma_f32_16x16x32_bf16 v[24:27], v[194:197], v[178:181], v[24:27]
	v_mfma_f32_16x16x32_bf16 v[20:23], v[202:205], v[178:181], v[20:23]
	v_mfma_f32_16x16x32_bf16 v[16:19], v[194:197], v[186:189], v[16:19]
	v_mfma_f32_16x16x32_bf16 v[12:15], v[202:205], v[186:189], v[12:15]
	v_mfma_f32_16x16x32_bf16 v[64:67], v[198:201], v[166:169], v[64:67]
	v_mfma_f32_16x16x32_bf16 v[60:63], v[206:209], v[166:169], v[60:63]
	v_mfma_f32_16x16x32_bf16 v[44:47], v[198:201], v[174:177], v[44:47]
	v_mfma_f32_16x16x32_bf16 v[40:43], v[206:209], v[174:177], v[40:43]
	v_mfma_f32_16x16x32_bf16 v[24:27], v[198:201], v[182:185], v[24:27]
	v_mfma_f32_16x16x32_bf16 v[20:23], v[206:209], v[182:185], v[20:23]
	v_mfma_f32_16x16x32_bf16 v[16:19], v[198:201], v[190:193], v[16:19]
	v_mfma_f32_16x16x32_bf16 v[12:15], v[206:209], v[190:193], v[12:15]
	s_setprio 0
	s_barrier
	ds_read_b128 v[146:149], v144
	ds_read_b128 v[150:153], v144 offset:1024
	ds_read_b128 v[154:157], v144 offset:2048
	ds_read_b128 v[158:161], v144 offset:3072
	s_add_u32 s14, s14, 0x20000
	s_addc_u32 s15, s15, 0
	s_mov_b32 m0, s25
	v_lshl_add_u64 v[194:195], s[14:15], 0, v[134:135]
	ds_read_b128 v[162:165], v142 offset:32768
	ds_read_b128 v[166:169], v142 offset:33792
	ds_read_b128 v[170:173], v142 offset:34816
	ds_read_b128 v[174:177], v142 offset:35840
	ds_read_b128 v[178:181], v142 offset:36864
	ds_read_b128 v[182:185], v142 offset:37888
	ds_read_b128 v[186:189], v142 offset:38912
	ds_read_b128 v[190:193], v142 offset:39936
	global_load_lds_dwordx4 v[194:195], off
	v_lshl_add_u64 v[194:195], s[14:15], 0, v[130:131]
	s_mov_b32 m0, s27
	s_nop 0
	global_load_lds_dwordx4 v[194:195], off
	s_waitcnt lgkmcnt(8)
	s_barrier
	s_waitcnt lgkmcnt(0)
	s_setprio 1
	s_waitcnt lgkmcnt(0)
	v_mfma_f32_16x16x32_bf16 v[104:107], v[146:149], v[162:165], v[104:107]
	v_mfma_f32_16x16x32_bf16 v[108:111], v[154:157], v[162:165], v[108:111]
	v_mfma_f32_16x16x32_bf16 v[124:127], v[146:149], v[170:173], v[124:127]
	v_mfma_f32_16x16x32_bf16 v[116:119], v[154:157], v[170:173], v[116:119]
	v_mfma_f32_16x16x32_bf16 v[96:99], v[146:149], v[178:181], v[96:99]
	v_mfma_f32_16x16x32_bf16 v[88:91], v[154:157], v[178:181], v[88:91]
	v_mfma_f32_16x16x32_bf16 v[80:83], v[146:149], v[186:189], v[80:83]
	v_mfma_f32_16x16x32_bf16 v[72:75], v[154:157], v[186:189], v[72:75]
	v_mfma_f32_16x16x32_bf16 v[104:107], v[150:153], v[166:169], v[104:107]
	v_mfma_f32_16x16x32_bf16 v[108:111], v[158:161], v[166:169], v[108:111]
	v_mfma_f32_16x16x32_bf16 v[124:127], v[150:153], v[174:177], v[124:127]
	v_mfma_f32_16x16x32_bf16 v[116:119], v[158:161], v[174:177], v[116:119]
	v_mfma_f32_16x16x32_bf16 v[96:99], v[150:153], v[182:185], v[96:99]
	v_mfma_f32_16x16x32_bf16 v[88:91], v[158:161], v[182:185], v[88:91]
	v_mfma_f32_16x16x32_bf16 v[80:83], v[150:153], v[190:193], v[80:83]
	v_mfma_f32_16x16x32_bf16 v[72:75], v[158:161], v[190:193], v[72:75]
	s_setprio 0
	s_barrier
	s_mov_b32 m0, s46
	v_lshl_add_u64 v[210:211], v[210:211], 0, s[4:5]
	ds_read_b128 v[194:197], v145
	ds_read_b128 v[198:201], v145 offset:1024
	ds_read_b128 v[202:205], v145 offset:2048
	ds_read_b128 v[206:209], v145 offset:3072
	global_load_lds_dwordx4 v[210:211], off
	v_lshl_add_u64 v[210:211], v[212:213], 0, s[4:5]
	s_mov_b32 m0, s47
	s_nop 0
	global_load_lds_dwordx4 v[210:211], off
	s_barrier
	s_waitcnt lgkmcnt(0)
	s_setprio 1
	s_waitcnt lgkmcnt(0)
	v_mfma_f32_16x16x32_bf16 v[112:115], v[194:197], v[162:165], v[112:115]
	v_mfma_f32_16x16x32_bf16 v[120:123], v[202:205], v[162:165], v[120:123]
	v_mfma_f32_16x16x32_bf16 v[100:103], v[194:197], v[170:173], v[100:103]
	v_mfma_f32_16x16x32_bf16 v[92:95], v[202:205], v[170:173], v[92:95]
	v_mfma_f32_16x16x32_bf16 v[84:87], v[194:197], v[178:181], v[84:87]
	v_mfma_f32_16x16x32_bf16 v[76:79], v[202:205], v[178:181], v[76:79]
	v_mfma_f32_16x16x32_bf16 v[68:71], v[194:197], v[186:189], v[68:71]
	v_mfma_f32_16x16x32_bf16 v[56:59], v[202:205], v[186:189], v[56:59]
	v_mfma_f32_16x16x32_bf16 v[112:115], v[198:201], v[166:169], v[112:115]
	v_mfma_f32_16x16x32_bf16 v[120:123], v[206:209], v[166:169], v[120:123]
	v_mfma_f32_16x16x32_bf16 v[100:103], v[198:201], v[174:177], v[100:103]
	v_mfma_f32_16x16x32_bf16 v[92:95], v[206:209], v[174:177], v[92:95]
	v_mfma_f32_16x16x32_bf16 v[84:87], v[198:201], v[182:185], v[84:87]
	v_mfma_f32_16x16x32_bf16 v[76:79], v[206:209], v[182:185], v[76:79]
	v_mfma_f32_16x16x32_bf16 v[68:71], v[198:201], v[190:193], v[68:71]
	v_mfma_f32_16x16x32_bf16 v[56:59], v[206:209], v[190:193], v[56:59]
	s_setprio 0
	s_mov_b32 m0, s29
	v_lshl_add_u64 v[210:211], v[214:215], 0, s[4:5]
	s_barrier
; #define PG8_STAGE(bufoff, gbase, voff) do { _Pragma("unroll") for (int _i = 0; _i < 2; ++_i) \
;         __builtin_amdgcn_global_load_lds((const unsigned*)((const char*)(gbase) + (voff)[_i]), (LAS unsigned*)(lds + (bufoff) + ldsw + _i * 8192), 16, 0, 0); } while (0)
; #define PG8_LDA(dst, b, h) do { _Pragma("unroll") for (int m = 0; m < 4; ++m) _Pragma("unroll") for (int k = 0; k < 2; ++k) dst[m][k] = *(const LAS bf16x8*)(lds + PG8_SA(b, h) + aoff + m * 2048 + k * 1024); } while (0)
; #define PG8_MMA(ai, bj, At, Bt) do { __builtin_amdgcn_s_setprio(1); _Pragma("unroll") for (int m = 0; m < 4; ++m) _Pragma("unroll") for (int n = 0; n < 2; ++n) _Pragma("unroll") for (int k = 0; k < 2; ++k) \
;         acc[ai][bj][m][n] = __builtin_amdgcn_mfma_f32_16x16x32_bf16(Bt[n][k], At[m][k], acc[ai][bj][m][n], 0, 0, 0); __builtin_amdgcn_s_setprio(0); } while (0)
; #define PG8_WAIT_V(n) asm volatile("s_waitcnt vmcnt(" #n ")" ::: "memory")
; #define PG8_WAIT_L(n) asm volatile("s_waitcnt lgkmcnt(" #n ")" ::: "memory")
; #define PG8_BAR __builtin_amdgcn_s_barrier()
; #define PG8_SCHED __builtin_amdgcn_sched_barrier(0)
; template <class Epi, class Sched, bool ZERO>
; __device__ __forceinline__ void gemm_phase_acc(LAS unsigned char* lds, const Gemm g, const Sched& S, const Epi& E, f32x4 (&acc)[2][2][4][2]) {
;     ...
;             PG8_LDA(At, 1, 1); PG8_STAGE(PG8_SA(1, 0), a3, voffA);
;             PG8_BAR; PG8_WAIT_L(0); PG8_MMA(1, 0, At, B0); PG8_BAR; PG8_SCHED;
;             PG8_STAGE(PG8_SB(1, 1), b3 + hstep, voffB);
;             PG8_WAIT_V(6); PG8_BAR; PG8_MMA(1, 1, At, B1); PG8_BAR;
;     ...
;     PG8_WAIT_V(0);
;     __device__ __forceinline__ void operator()(f32x4 (&acc)[2][2][4][2], const Unit& u, int wr, int wc, int fr, int fq) const {
;         const bf16_t* gr = (const bf16_t*)(ws + OFF_GB) + (size_t)(u.pm * 8 + 4 + u.pn) * 65536 + ((wr * 4 + wc) * 16 * 64 + (fq * 16 + fr)) * 8;
;         const int row0 = u.pm * 256 + wr * 64 + fr, col0 = wc * 32 + 8 * fq;
; #pragma unroll
;         for (int ai = 0; ai < 2; ++ai) {
;             u32x4 g8[4][2];
; #pragma unroll
;             for (int m = 0; m < 4; ++m)
; #pragma unroll
;                 for (int bj = 0; bj < 2; ++bj) g8[m][bj] = __builtin_nontemporal_load((const u32x4*)(gr + ((ai * 4 + m) * 2 + bj) * 512));
	ds_read_b128 v[162:165], v142 offset:49152
	ds_read_b128 v[166:169], v142 offset:50176
	ds_read_b128 v[170:173], v142 offset:51200
	ds_read_b128 v[174:177], v142 offset:52224
	ds_read_b128 v[178:181], v142 offset:53248
	ds_read_b128 v[182:185], v142 offset:54272
	ds_read_b128 v[186:189], v142 offset:55296
	ds_read_b128 v[190:193], v142 offset:56320
	global_load_lds_dwordx4 v[210:211], off
	v_lshl_add_u64 v[210:211], v[216:217], 0, s[4:5]
	s_mov_b32 m0, s30
	s_nop 0
	global_load_lds_dwordx4 v[210:211], off
	s_barrier
	s_waitcnt lgkmcnt(0)
	s_setprio 1
	s_waitcnt lgkmcnt(0)
	v_mfma_f32_16x16x32_bf16 v[52:55], v[146:149], v[162:165], v[52:55]
	v_mfma_f32_16x16x32_bf16 v[48:51], v[154:157], v[162:165], v[48:51]
	v_mfma_f32_16x16x32_bf16 v[36:39], v[146:149], v[170:173], v[36:39]
	v_mfma_f32_16x16x32_bf16 v[32:35], v[154:157], v[170:173], v[32:35]
	v_mfma_f32_16x16x32_bf16 v[28:31], v[146:149], v[178:181], v[28:31]
	v_mfma_f32_16x16x32_bf16 v[8:11], v[154:157], v[178:181], v[8:11]
	v_mfma_f32_16x16x32_bf16 v[4:7], v[146:149], v[186:189], v[4:7]
	v_mfma_f32_16x16x32_bf16 v[0:3], v[154:157], v[186:189], v[0:3]
	v_mfma_f32_16x16x32_bf16 v[52:55], v[150:153], v[166:169], v[52:55]
	v_mfma_f32_16x16x32_bf16 v[48:51], v[158:161], v[166:169], v[48:51]
	v_mfma_f32_16x16x32_bf16 v[36:39], v[150:153], v[174:177], v[36:39]
	v_mfma_f32_16x16x32_bf16 v[32:35], v[158:161], v[174:177], v[32:35]
	v_mfma_f32_16x16x32_bf16 v[28:31], v[150:153], v[182:185], v[28:31]
	v_mfma_f32_16x16x32_bf16 v[8:11], v[158:161], v[182:185], v[8:11]
	v_mfma_f32_16x16x32_bf16 v[4:7], v[150:153], v[190:193], v[4:7]
	v_mfma_f32_16x16x32_bf16 v[0:3], v[158:161], v[190:193], v[0:3]
	s_setprio 0
	s_barrier
	s_add_u32 s10, s10, 0x20080
	s_addc_u32 s11, s11, 0
	s_mov_b32 m0, s48
	v_lshl_add_u64 v[146:147], s[10:11], 0, v[132:133]
	global_load_lds_dwordx4 v[146:147], off
	v_lshl_add_u64 v[146:147], s[10:11], 0, v[128:129]
	s_mov_b32 m0, s49
	s_nop 0
	global_load_lds_dwordx4 v[146:147], off
	s_waitcnt vmcnt(6)
	s_barrier
	s_setprio 1
	v_mfma_f32_16x16x32_bf16 v[64:67], v[194:197], v[162:165], v[64:67]
	v_mfma_f32_16x16x32_bf16 v[60:63], v[202:205], v[162:165], v[60:63]
	v_mfma_f32_16x16x32_bf16 v[44:47], v[194:197], v[170:173], v[44:47]
	v_mfma_f32_16x16x32_bf16 v[40:43], v[202:205], v[170:173], v[40:43]
	v_mfma_f32_16x16x32_bf16 v[24:27], v[194:197], v[178:181], v[24:27]
	v_mfma_f32_16x16x32_bf16 v[20:23], v[202:205], v[178:181], v[20:23]
	v_mfma_f32_16x16x32_bf16 v[16:19], v[194:197], v[186:189], v[16:19]
	v_mfma_f32_16x16x32_bf16 v[12:15], v[202:205], v[186:189], v[12:15]
	v_mfma_f32_16x16x32_bf16 v[64:67], v[198:201], v[166:169], v[64:67]
	v_mfma_f32_16x16x32_bf16 v[60:63], v[206:209], v[166:169], v[60:63]
	v_mfma_f32_16x16x32_bf16 v[44:47], v[198:201], v[174:177], v[44:47]
	v_mfma_f32_16x16x32_bf16 v[40:43], v[206:209], v[174:177], v[40:43]
	v_mfma_f32_16x16x32_bf16 v[24:27], v[198:201], v[182:185], v[24:27]
	v_mfma_f32_16x16x32_bf16 v[20:23], v[206:209], v[182:185], v[20:23]
	v_mfma_f32_16x16x32_bf16 v[16:19], v[198:201], v[190:193], v[16:19]
	v_mfma_f32_16x16x32_bf16 v[12:15], v[206:209], v[190:193], v[12:15]
	s_setprio 0
	s_add_i32 s39, s39, 2
	s_add_u32 s8, s8, 0x100
	s_addc_u32 s9, s9, 0
	s_cmp_gt_u32 s39, 5
	s_barrier
	s_cbranch_scc0 .LBB0_973
	s_lshl_b32 s0, s17, 12
	s_lshl_b32 s1, s28, 10
	s_or_b32 s0, s1, s0
	v_and_or_b32 v128, v140, 63, s0
	s_or_b32 s0, s26, s34
	v_lshlrev_b32_e32 v128, 3, v128
	s_or_b32 s2, s0, 4
	v_ashrrev_i32_e32 v129, 31, v128
	s_ashr_i32 s3, s2, 31
	v_lshl_add_u64 v[128:129], v[128:129], 1, s[12:13]
	s_lshl_b64 s[2:3], s[2:3], 17
	v_lshl_add_u64 v[128:129], v[128:129], 0, s[2:3]
	s_movk_i32 s1, 0x1000
	v_add_co_u32_e32 v130, vcc, s1, v128
	s_movk_i32 s1, 0x2000
	s_nop 0
	v_addc_co_u32_e32 v131, vcc, 0, v129, vcc
	v_add_co_u32_e32 v136, vcc, s1, v128
	global_load_dwordx4 v[188:191], v[128:129], off nt
	global_load_dwordx4 v[184:187], v[128:129], off offset:1024 nt
	global_load_dwordx4 v[180:183], v[128:129], off offset:2048 nt
	global_load_dwordx4 v[176:179], v[128:129], off offset:3072 nt
	v_addc_co_u32_e32 v137, vcc, 0, v129, vcc
	v_add_co_u32_e32 v138, vcc, 0x3000, v128
	global_load_dwordx4 v[168:171], v[130:131], off offset:1024 nt
	global_load_dwordx4 v[164:167], v[130:131], off offset:2048 nt
	global_load_dwordx4 v[160:163], v[136:137], off nt
	global_load_dwordx4 v[156:159], v[136:137], off offset:1024 nt
	global_load_dwordx4 v[152:155], v[136:137], off offset:2048 nt
	global_load_dwordx4 v[148:151], v[136:137], off offset:3072 nt
	v_addc_co_u32_e32 v139, vcc, 0, v129, vcc
	global_load_dwordx4 v[128:131], v[130:131], off offset:3072 nt
	s_nop 0
	global_load_dwordx4 v[132:135], v[138:139], off nt
	global_load_dwordx4 v[144:147], v[138:139], off offset:1024 nt
	global_load_dwordx4 v[140:143], v[138:139], off offset:2048 nt
	global_load_dwordx4 v[172:175], v[136:137], off offset:-4096 nt
	s_nop 0
	global_load_dwordx4 v[136:139], v[138:139], off offset:3072 nt
	s_cmpk_lt_u32 s16, 0x100
	s_cbranch_scc0 .LBB0_976
	s_barrier

; #define PG8_STAGE(bufoff, gbase, voff) do { _Pragma("unroll") for (int _i = 0; _i < 2; ++_i) \
;         __builtin_amdgcn_global_load_lds((const unsigned*)((const char*)(gbase) + (voff)[_i]), (LAS unsigned*)(lds + (bufoff) + ldsw + _i * 8192), 16, 0, 0); } while (0)
; #define PG8_LDA(dst, b, h) do { _Pragma("unroll") for (int m = 0; m < 4; ++m) _Pragma("unroll") for (int k = 0; k < 2; ++k) dst[m][k] = *(const LAS bf16x8*)(lds + PG8_SA(b, h) + aoff + m * 2048 + k * 1024); } while (0)
; #define PG8_LDB(dst, b, h) do { _Pragma("unroll") for (int n = 0; n < 2; ++n) _Pragma("unroll") for (int k = 0; k < 2; ++k) dst[n][k] = *(const LAS bf16x8*)(lds + PG8_SB(b, h) + boff + n * 2048 + k * 1024); } while (0)
; #define PG8_MMA(ai, bj, At, Bt) do { __builtin_amdgcn_s_setprio(1); _Pragma("unroll") for (int m = 0; m < 4; ++m) _Pragma("unroll") for (int n = 0; n < 2; ++n) _Pragma("unroll") for (int k = 0; k < 2; ++k) \
;         acc[ai][bj][m][n] = __builtin_amdgcn_mfma_f32_16x16x32_bf16(Bt[n][k], At[m][k], acc[ai][bj][m][n], 0, 0, 0); __builtin_amdgcn_s_setprio(0); } while (0)
; #define PG8_WAIT_L(n) asm volatile("s_waitcnt lgkmcnt(" #n ")" ::: "memory")
; #define PG8_BAR __builtin_amdgcn_s_barrier()
; #define PG8_SCHED __builtin_amdgcn_sched_barrier(0)
; template <class Epi, class Sched, bool ZERO>
; __device__ __forceinline__ void gemm_phase_acc(LAS unsigned char* lds, const Gemm g, const Sched& S, const Epi& E, f32x4 (&acc)[2][2][4][2]) {
;     ...
;             PG8_LDB(B0, 0, 0); PG8_SCHED; PG8_LDA(At, 0, 0); PG8_STAGE(PG8_SA(1, 1), a1 + hstep, voffA);
;             PG8_WAIT_L(8); PG8_BAR; PG8_WAIT_L(0); PG8_MMA(0, 0, At, B0); PG8_BAR; PG8_SCHED;
;             PG8_LDB(B1, 0, 1); PG8_STAGE(PG8_SB(0, 0), b2, voffB);
;             PG8_BAR; PG8_WAIT_L(0); PG8_MMA(0, 1, At, B1); PG8_BAR;
;             PG8_LDA(At, 0, 1); PG8_STAGE(PG8_SA(0, 0), a2, voffA);
;             PG8_BAR; PG8_WAIT_L(0); PG8_MMA(1, 0, At, B0); PG8_BAR; PG8_SCHED;
.LBB0_979:
	v_add_u32_e32 v17, s35, v210
	s_add_u32 s10, s4, s8
	ds_read_b128 v[136:139], v17
	ds_read_b128 v[140:143], v17 offset:1024
	ds_read_b128 v[144:147], v17 offset:2048
	ds_read_b128 v[148:151], v17 offset:3072
	s_addc_u32 s11, s5, s9
	s_add_u32 s10, s10, 0x100
	s_addc_u32 s11, s11, 0
	s_add_u32 s50, s31, s8
	s_addc_u32 s51, s38, s9
	s_cmpk_eq_i32 s8, 0x700
	s_cselect_b32 s15, s5, s11
	s_cselect_b32 s14, s4, s10
	s_cselect_b32 s11, s3, s51
	s_cselect_b32 s10, s2, s50
	s_mov_b32 m0, s40
	v_lshl_add_u64 v[18:19], v[12:13], 0, s[8:9]
	ds_read_b128 v[152:155], v16
	ds_read_b128 v[156:159], v16 offset:1024
	ds_read_b128 v[160:163], v16 offset:2048
	ds_read_b128 v[164:167], v16 offset:3072
	ds_read_b128 v[168:171], v16 offset:4096
	ds_read_b128 v[172:175], v16 offset:5120
	ds_read_b128 v[176:179], v16 offset:6144
	ds_read_b128 v[180:183], v16 offset:7168
	global_load_lds_dwordx4 v[18:19], off
	v_lshl_add_u64 v[18:19], v[14:15], 0, s[8:9]
	s_mov_b32 m0, s41
	s_nop 0
	global_load_lds_dwordx4 v[18:19], off
	s_waitcnt lgkmcnt(8)
	s_barrier
	s_waitcnt lgkmcnt(0)
	s_setprio 1
	s_waitcnt lgkmcnt(0)
	v_mfma_f32_16x16x32_bf16 v[104:107], v[136:139], v[152:155], v[104:107]
	v_mfma_f32_16x16x32_bf16 v[108:111], v[144:147], v[152:155], v[108:111]
	v_mfma_f32_16x16x32_bf16 v[124:127], v[136:139], v[160:163], v[124:127]
	v_mfma_f32_16x16x32_bf16 v[116:119], v[144:147], v[160:163], v[116:119]
	v_mfma_f32_16x16x32_bf16 v[96:99], v[136:139], v[168:171], v[96:99]
	v_mfma_f32_16x16x32_bf16 v[88:91], v[144:147], v[168:171], v[88:91]
	v_mfma_f32_16x16x32_bf16 v[80:83], v[136:139], v[176:179], v[80:83]
	v_mfma_f32_16x16x32_bf16 v[72:75], v[144:147], v[176:179], v[72:75]
	v_mfma_f32_16x16x32_bf16 v[104:107], v[140:143], v[156:159], v[104:107]
	v_mfma_f32_16x16x32_bf16 v[108:111], v[148:151], v[156:159], v[108:111]
	v_mfma_f32_16x16x32_bf16 v[124:127], v[140:143], v[164:167], v[124:127]
	v_mfma_f32_16x16x32_bf16 v[116:119], v[148:151], v[164:167], v[116:119]
	v_mfma_f32_16x16x32_bf16 v[96:99], v[140:143], v[172:175], v[96:99]
	v_mfma_f32_16x16x32_bf16 v[88:91], v[148:151], v[172:175], v[88:91]
	v_mfma_f32_16x16x32_bf16 v[80:83], v[140:143], v[180:183], v[80:83]
	v_mfma_f32_16x16x32_bf16 v[72:75], v[148:151], v[180:183], v[72:75]
	s_setprio 0
	s_barrier
	s_mov_b32 m0, s42
	v_add_u32_e32 v17, s22, v210
	v_lshl_add_u64 v[212:213], s[10:11], 0, v[196:197]
	ds_read_b128 v[184:187], v17
	ds_read_b128 v[188:191], v17 offset:1024
	ds_read_b128 v[200:203], v17 offset:2048
	ds_read_b128 v[204:207], v17 offset:3072
	global_load_lds_dwordx4 v[212:213], off
	v_lshl_add_u64 v[214:215], s[10:11], 0, v[192:193]
	s_mov_b32 m0, s43
	s_nop 0
	global_load_lds_dwordx4 v[214:215], off
	s_barrier
	s_waitcnt lgkmcnt(0)
	s_setprio 1
	s_waitcnt lgkmcnt(0)
	v_mfma_f32_16x16x32_bf16 v[112:115], v[184:187], v[152:155], v[112:115]
	v_mfma_f32_16x16x32_bf16 v[120:123], v[200:203], v[152:155], v[120:123]
	v_mfma_f32_16x16x32_bf16 v[100:103], v[184:187], v[160:163], v[100:103]
	v_mfma_f32_16x16x32_bf16 v[92:95], v[200:203], v[160:163], v[92:95]
	v_mfma_f32_16x16x32_bf16 v[84:87], v[184:187], v[168:171], v[84:87]
	v_mfma_f32_16x16x32_bf16 v[76:79], v[200:203], v[168:171], v[76:79]
	v_mfma_f32_16x16x32_bf16 v[68:71], v[184:187], v[176:179], v[68:71]
	v_mfma_f32_16x16x32_bf16 v[128:131], v[200:203], v[176:179], v[128:131]
	v_mfma_f32_16x16x32_bf16 v[112:115], v[188:191], v[156:159], v[112:115]
	v_mfma_f32_16x16x32_bf16 v[120:123], v[204:207], v[156:159], v[120:123]
	v_mfma_f32_16x16x32_bf16 v[100:103], v[188:191], v[164:167], v[100:103]
	v_mfma_f32_16x16x32_bf16 v[92:95], v[204:207], v[164:167], v[92:95]
	v_mfma_f32_16x16x32_bf16 v[84:87], v[188:191], v[172:175], v[84:87]
	v_mfma_f32_16x16x32_bf16 v[76:79], v[204:207], v[172:175], v[76:79]
	v_mfma_f32_16x16x32_bf16 v[68:71], v[188:191], v[180:183], v[68:71]
	v_mfma_f32_16x16x32_bf16 v[128:131], v[204:207], v[180:183], v[128:131]
	s_setprio 0
	s_mov_b32 m0, s24
	v_lshl_add_u64 v[216:217], s[14:15], 0, v[198:199]
	s_barrier
	ds_read_b128 v[152:155], v16 offset:16384
	ds_read_b128 v[156:159], v16 offset:17408
	ds_read_b128 v[160:163], v16 offset:18432
	ds_read_b128 v[164:167], v16 offset:19456
	ds_read_b128 v[168:171], v16 offset:20480
	ds_read_b128 v[172:175], v16 offset:21504
	ds_read_b128 v[176:179], v16 offset:22528
	ds_read_b128 v[180:183], v16 offset:23552
	global_load_lds_dwordx4 v[216:217], off
	v_lshl_add_u64 v[218:219], s[14:15], 0, v[194:195]
	s_mov_b32 m0, s25
	s_nop 0
	global_load_lds_dwordx4 v[218:219], off
	s_barrier
	s_waitcnt lgkmcnt(0)
	s_setprio 1
	s_waitcnt lgkmcnt(0)
	v_mfma_f32_16x16x32_bf16 v[52:55], v[136:139], v[152:155], v[52:55]
	v_mfma_f32_16x16x32_bf16 v[56:59], v[144:147], v[152:155], v[56:59]
	v_mfma_f32_16x16x32_bf16 v[36:39], v[136:139], v[160:163], v[36:39]
	v_mfma_f32_16x16x32_bf16 v[64:67], v[144:147], v[160:163], v[64:67]
	v_mfma_f32_16x16x32_bf16 v[28:31], v[136:139], v[168:171], v[28:31]
	v_mfma_f32_16x16x32_bf16 v[132:135], v[144:147], v[168:171], v[132:135]
	v_mfma_f32_16x16x32_bf16 v[18:21], v[136:139], v[176:179], v[20:23]
	v_mfma_f32_16x16x32_bf16 v[8:11], v[144:147], v[176:179], v[8:11]
	v_mfma_f32_16x16x32_bf16 v[52:55], v[140:143], v[156:159], v[52:55]
	v_mfma_f32_16x16x32_bf16 v[56:59], v[148:151], v[156:159], v[56:59]
	v_mfma_f32_16x16x32_bf16 v[36:39], v[140:143], v[164:167], v[36:39]
	v_mfma_f32_16x16x32_bf16 v[64:67], v[148:151], v[164:167], v[64:67]
	v_mfma_f32_16x16x32_bf16 v[28:31], v[140:143], v[172:175], v[28:31]
	v_mfma_f32_16x16x32_bf16 v[132:135], v[148:151], v[172:175], v[132:135]
	v_mfma_f32_16x16x32_bf16 v[18:21], v[140:143], v[180:183], v[18:21]
	v_mfma_f32_16x16x32_bf16 v[8:11], v[148:151], v[180:183], v[8:11]
	s_setprio 0
	s_barrier
; #define PG8_STAGE(bufoff, gbase, voff) do { _Pragma("unroll") for (int _i = 0; _i < 2; ++_i) \
;         __builtin_amdgcn_global_load_lds((const unsigned*)((const char*)(gbase) + (voff)[_i]), (LAS unsigned*)(lds + (bufoff) + ldsw + _i * 8192), 16, 0, 0); } while (0)
; #define PG8_LDA(dst, b, h) do { _Pragma("unroll") for (int m = 0; m < 4; ++m) _Pragma("unroll") for (int k = 0; k < 2; ++k) dst[m][k] = *(const LAS bf16x8*)(lds + PG8_SA(b, h) + aoff + m * 2048 + k * 1024); } while (0)
; #define PG8_LDB(dst, b, h) do { _Pragma("unroll") for (int n = 0; n < 2; ++n) _Pragma("unroll") for (int k = 0; k < 2; ++k) dst[n][k] = *(const LAS bf16x8*)(lds + PG8_SB(b, h) + boff + n * 2048 + k * 1024); } while (0)
; #define PG8_MMA(ai, bj, At, Bt) do { __builtin_amdgcn_s_setprio(1); _Pragma("unroll") for (int m = 0; m < 4; ++m) _Pragma("unroll") for (int n = 0; n < 2; ++n) _Pragma("unroll") for (int k = 0; k < 2; ++k) \
;         acc[ai][bj][m][n] = __builtin_amdgcn_mfma_f32_16x16x32_bf16(Bt[n][k], At[m][k], acc[ai][bj][m][n], 0, 0, 0); __builtin_amdgcn_s_setprio(0); } while (0)
; #define PG8_WAIT_V(n) asm volatile("s_waitcnt vmcnt(" #n ")" ::: "memory")
; #define PG8_WAIT_L(n) asm volatile("s_waitcnt lgkmcnt(" #n ")" ::: "memory")
; #define PG8_BAR __builtin_amdgcn_s_barrier()
; #define PG8_SCHED __builtin_amdgcn_sched_barrier(0)
; template <class Epi, class Sched, bool ZERO>
; __device__ __forceinline__ void gemm_phase_acc(LAS unsigned char* lds, const Gemm g, const Sched& S, const Epi& E, f32x4 (&acc)[2][2][4][2]) {
;     ...
;             PG8_STAGE(PG8_SB(0, 1), b2 + hstep, voffB);
;             PG8_WAIT_V(6); PG8_BAR; PG8_MMA(1, 1, At, B1); PG8_BAR;
;             PG8_LDB(B0, 1, 0); PG8_SCHED; PG8_LDA(At, 1, 0); PG8_STAGE(PG8_SA(0, 1), a2 + hstep, voffA);
;             PG8_WAIT_L(8); PG8_BAR; PG8_WAIT_L(0); PG8_MMA(0, 0, At, B0); PG8_BAR; PG8_SCHED;
;             PG8_LDB(B1, 1, 1); PG8_STAGE(PG8_SB(1, 0), b3, voffB);
;             PG8_BAR; PG8_WAIT_L(0); PG8_MMA(0, 1, At, B1); PG8_BAR;
	s_add_u32 s50, s10, 0x40000
	s_addc_u32 s51, s11, 0
	s_mov_b32 m0, s44
	v_lshl_add_u64 v[22:23], s[50:51], 0, v[196:197]
	global_load_lds_dwordx4 v[22:23], off
	v_lshl_add_u64 v[22:23], s[50:51], 0, v[192:193]
	s_mov_b32 m0, s45
	s_nop 0
	global_load_lds_dwordx4 v[22:23], off
	s_waitcnt vmcnt(6)
	s_barrier
	s_setprio 1
	v_mfma_f32_16x16x32_bf16 v[48:51], v[184:187], v[152:155], v[48:51]
	v_mfma_f32_16x16x32_bf16 v[60:63], v[200:203], v[152:155], v[60:63]
	v_mfma_f32_16x16x32_bf16 v[32:35], v[184:187], v[160:163], v[32:35]
	v_mfma_f32_16x16x32_bf16 v[40:43], v[200:203], v[160:163], v[40:43]
	v_mfma_f32_16x16x32_bf16 v[44:47], v[184:187], v[168:171], v[44:47]
	v_mfma_f32_16x16x32_bf16 v[22:25], v[200:203], v[168:171], v[24:27]
	v_mfma_f32_16x16x32_bf16 v[4:7], v[184:187], v[176:179], v[4:7]
	v_mfma_f32_16x16x32_bf16 v[0:3], v[200:203], v[176:179], v[0:3]
	v_mfma_f32_16x16x32_bf16 v[48:51], v[188:191], v[156:159], v[48:51]
	v_mfma_f32_16x16x32_bf16 v[60:63], v[204:207], v[156:159], v[60:63]
	v_mfma_f32_16x16x32_bf16 v[32:35], v[188:191], v[164:167], v[32:35]
	v_mfma_f32_16x16x32_bf16 v[40:43], v[204:207], v[164:167], v[40:43]
	v_mfma_f32_16x16x32_bf16 v[44:47], v[188:191], v[172:175], v[44:47]
	v_mfma_f32_16x16x32_bf16 v[24:27], v[204:207], v[172:175], v[22:25]
	v_mfma_f32_16x16x32_bf16 v[4:7], v[188:191], v[180:183], v[4:7]
	v_mfma_f32_16x16x32_bf16 v[0:3], v[204:207], v[180:183], v[0:3]
	s_setprio 0
	v_add_u32_e32 v17, s23, v210
	s_barrier
	ds_read_b128 v[136:139], v17
	ds_read_b128 v[140:143], v17 offset:1024
	ds_read_b128 v[144:147], v17 offset:2048
	ds_read_b128 v[148:151], v17 offset:3072
	s_add_u32 s14, s14, 0x40000
	s_addc_u32 s15, s15, 0
	s_mov_b32 m0, s26
	v_lshl_add_u64 v[22:23], s[14:15], 0, v[198:199]
	ds_read_b128 v[152:155], v16 offset:32768
	ds_read_b128 v[156:159], v16 offset:33792
	ds_read_b128 v[160:163], v16 offset:34816
	ds_read_b128 v[164:167], v16 offset:35840
	ds_read_b128 v[168:171], v16 offset:36864
	ds_read_b128 v[172:175], v16 offset:37888
	ds_read_b128 v[176:179], v16 offset:38912
	ds_read_b128 v[180:183], v16 offset:39936
	global_load_lds_dwordx4 v[22:23], off
	v_lshl_add_u64 v[22:23], s[14:15], 0, v[194:195]
	s_mov_b32 m0, s27
	s_nop 0
	global_load_lds_dwordx4 v[22:23], off
	s_waitcnt lgkmcnt(8)
	s_barrier
	s_waitcnt lgkmcnt(0)
	s_setprio 1
	s_waitcnt lgkmcnt(0)
	v_mfma_f32_16x16x32_bf16 v[104:107], v[136:139], v[152:155], v[104:107]
	v_mfma_f32_16x16x32_bf16 v[108:111], v[144:147], v[152:155], v[108:111]
	v_mfma_f32_16x16x32_bf16 v[124:127], v[136:139], v[160:163], v[124:127]
	v_mfma_f32_16x16x32_bf16 v[116:119], v[144:147], v[160:163], v[116:119]
	v_mfma_f32_16x16x32_bf16 v[96:99], v[136:139], v[168:171], v[96:99]
	v_mfma_f32_16x16x32_bf16 v[88:91], v[144:147], v[168:171], v[88:91]
	v_mfma_f32_16x16x32_bf16 v[80:83], v[136:139], v[176:179], v[80:83]
	v_mfma_f32_16x16x32_bf16 v[72:75], v[144:147], v[176:179], v[72:75]
	v_mfma_f32_16x16x32_bf16 v[104:107], v[140:143], v[156:159], v[104:107]
	v_mfma_f32_16x16x32_bf16 v[108:111], v[148:151], v[156:159], v[108:111]
	v_mfma_f32_16x16x32_bf16 v[124:127], v[140:143], v[164:167], v[124:127]
	v_mfma_f32_16x16x32_bf16 v[116:119], v[148:151], v[164:167], v[116:119]
	v_mfma_f32_16x16x32_bf16 v[96:99], v[140:143], v[172:175], v[96:99]
	v_mfma_f32_16x16x32_bf16 v[88:91], v[148:151], v[172:175], v[88:91]
	v_mfma_f32_16x16x32_bf16 v[80:83], v[140:143], v[180:183], v[80:83]
	v_mfma_f32_16x16x32_bf16 v[72:75], v[148:151], v[180:183], v[72:75]
	s_setprio 0
	s_barrier
	s_mov_b32 m0, s46
	v_add_u32_e32 v17, s33, v210
	v_lshl_add_u64 v[22:23], v[212:213], 0, s[6:7]
	ds_read_b128 v[184:187], v17
	ds_read_b128 v[188:191], v17 offset:1024
	ds_read_b128 v[200:203], v17 offset:2048
	ds_read_b128 v[204:207], v17 offset:3072
	global_load_lds_dwordx4 v[22:23], off
	v_lshl_add_u64 v[22:23], v[214:215], 0, s[6:7]
	s_mov_b32 m0, s47
	s_nop 0
	global_load_lds_dwordx4 v[22:23], off
	s_barrier
	s_waitcnt lgkmcnt(0)
	s_setprio 1
	s_waitcnt lgkmcnt(0)
	v_mfma_f32_16x16x32_bf16 v[112:115], v[184:187], v[152:155], v[112:115]
	v_mfma_f32_16x16x32_bf16 v[120:123], v[200:203], v[152:155], v[120:123]
	v_mfma_f32_16x16x32_bf16 v[100:103], v[184:187], v[160:163], v[100:103]
	v_mfma_f32_16x16x32_bf16 v[92:95], v[200:203], v[160:163], v[92:95]
	v_mfma_f32_16x16x32_bf16 v[84:87], v[184:187], v[168:171], v[84:87]
	v_mfma_f32_16x16x32_bf16 v[76:79], v[200:203], v[168:171], v[76:79]
	v_mfma_f32_16x16x32_bf16 v[68:71], v[184:187], v[176:179], v[68:71]
	v_mfma_f32_16x16x32_bf16 v[128:131], v[200:203], v[176:179], v[128:131]
	v_mfma_f32_16x16x32_bf16 v[112:115], v[188:191], v[156:159], v[112:115]
	v_mfma_f32_16x16x32_bf16 v[120:123], v[204:207], v[156:159], v[120:123]
	v_mfma_f32_16x16x32_bf16 v[100:103], v[188:191], v[164:167], v[100:103]
	v_mfma_f32_16x16x32_bf16 v[92:95], v[204:207], v[164:167], v[92:95]
	v_mfma_f32_16x16x32_bf16 v[84:87], v[188:191], v[172:175], v[84:87]
	v_mfma_f32_16x16x32_bf16 v[76:79], v[204:207], v[172:175], v[76:79]
	v_mfma_f32_16x16x32_bf16 v[68:71], v[188:191], v[180:183], v[68:71]
	v_mfma_f32_16x16x32_bf16 v[128:131], v[204:207], v[180:183], v[128:131]
	s_setprio 0
	s_mov_b32 m0, s29
	v_lshl_add_u64 v[22:23], v[216:217], 0, s[6:7]
	s_barrier
	ds_read_b128 v[152:155], v16 offset:49152
	ds_read_b128 v[156:159], v16 offset:50176
	ds_read_b128 v[160:163], v16 offset:51200
	ds_read_b128 v[164:167], v16 offset:52224
	ds_read_b128 v[168:171], v16 offset:53248
	ds_read_b128 v[172:175], v16 offset:54272
	ds_read_b128 v[176:179], v16 offset:55296
	ds_read_b128 v[180:183], v16 offset:56320
	global_load_lds_dwordx4 v[22:23], off
	v_lshl_add_u64 v[22:23], v[218:219], 0, s[6:7]
	s_mov_b32 m0, s30
	s_nop 0
	global_load_lds_dwordx4 v[22:23], off
	s_barrier
; #define PG8_STAGE(bufoff, gbase, voff) do { _Pragma("unroll") for (int _i = 0; _i < 2; ++_i) \
;         __builtin_amdgcn_global_load_lds((const unsigned*)((const char*)(gbase) + (voff)[_i]), (LAS unsigned*)(lds + (bufoff) + ldsw + _i * 8192), 16, 0, 0); } while (0)
; #define PG8_LDA(dst, b, h) do { _Pragma("unroll") for (int m = 0; m < 4; ++m) _Pragma("unroll") for (int k = 0; k < 2; ++k) dst[m][k] = *(const LAS bf16x8*)(lds + PG8_SA(b, h) + aoff + m * 2048 + k * 1024); } while (0)
; #define PG8_MMA(ai, bj, At, Bt) do { __builtin_amdgcn_s_setprio(1); _Pragma("unroll") for (int m = 0; m < 4; ++m) _Pragma("unroll") for (int n = 0; n < 2; ++n) _Pragma("unroll") for (int k = 0; k < 2; ++k) \
;         acc[ai][bj][m][n] = __builtin_amdgcn_mfma_f32_16x16x32_bf16(Bt[n][k], At[m][k], acc[ai][bj][m][n], 0, 0, 0); __builtin_amdgcn_s_setprio(0); } while (0)
; #define PG8_WAIT_V(n) asm volatile("s_waitcnt vmcnt(" #n ")" ::: "memory")
; #define PG8_WAIT_L(n) asm volatile("s_waitcnt lgkmcnt(" #n ")" ::: "memory")
; #define PG8_BAR __builtin_amdgcn_s_barrier()
; #define PG8_SCHED __builtin_amdgcn_sched_barrier(0)
; template <class Epi, class Sched, bool ZERO>
; __device__ __forceinline__ void gemm_phase_acc(LAS unsigned char* lds, const Gemm g, const Sched& S, const Epi& E, f32x4 (&acc)[2][2][4][2]) {
;     ...
;             PG8_LDA(At, 1, 1); PG8_STAGE(PG8_SA(1, 0), a3, voffA);
;             PG8_BAR; PG8_WAIT_L(0); PG8_MMA(1, 0, At, B0); PG8_BAR; PG8_SCHED;
;             PG8_STAGE(PG8_SB(1, 1), b3 + hstep, voffB);
;             PG8_WAIT_V(6); PG8_BAR; PG8_MMA(1, 1, At, B1); PG8_BAR;
;     __device__ __forceinline__ void operator()(f32x4 (&acc)[2][2][4][2], const Unit& u, int wr, int wc, int fr, int fq) const {
;     ...
;         const bf16_t* gb = (const bf16_t*)(ws + OFF_GB) + (size_t)(u.pm * 8 + u.pn) * 65536 + ((wr * 4 + wc) * 16 * 64 + (fq * 16 + fr)) * 8;
;         bf16_t* mg = (bf16_t*)(ws + OFF_MG) + u.pn * 256;
;         const int row0 = u.pm * 256 + wr * 64 + fr, col0 = wc * 32 + 8 * fq;
; #pragma unroll
;         for (int ai = 0; ai < 2; ++ai) {
;             u32x4 g8[4][2];
; #pragma unroll
;             for (int m = 0; m < 4; ++m)
; #pragma unroll
;                 for (int bj = 0; bj < 2; ++bj) g8[m][bj] = __builtin_nontemporal_load((const u32x4*)(gb + ((ai * 4 + m) * 2 + bj) * 512));
	s_waitcnt lgkmcnt(0)
	s_setprio 1
	s_waitcnt lgkmcnt(0)
	v_mfma_f32_16x16x32_bf16 v[52:55], v[136:139], v[152:155], v[52:55]
	v_mfma_f32_16x16x32_bf16 v[56:59], v[144:147], v[152:155], v[56:59]
	v_mfma_f32_16x16x32_bf16 v[36:39], v[136:139], v[160:163], v[36:39]
	v_mfma_f32_16x16x32_bf16 v[64:67], v[144:147], v[160:163], v[64:67]
	v_mfma_f32_16x16x32_bf16 v[28:31], v[136:139], v[168:171], v[28:31]
	v_mfma_f32_16x16x32_bf16 v[132:135], v[144:147], v[168:171], v[132:135]
	v_mfma_f32_16x16x32_bf16 v[18:21], v[136:139], v[176:179], v[18:21]
	v_mfma_f32_16x16x32_bf16 v[8:11], v[144:147], v[176:179], v[8:11]
	v_mfma_f32_16x16x32_bf16 v[52:55], v[140:143], v[156:159], v[52:55]
	v_mfma_f32_16x16x32_bf16 v[56:59], v[148:151], v[156:159], v[56:59]
	v_mfma_f32_16x16x32_bf16 v[36:39], v[140:143], v[164:167], v[36:39]
	v_mfma_f32_16x16x32_bf16 v[64:67], v[148:151], v[164:167], v[64:67]
	v_mfma_f32_16x16x32_bf16 v[28:31], v[140:143], v[172:175], v[28:31]
	v_mfma_f32_16x16x32_bf16 v[132:135], v[148:151], v[172:175], v[132:135]
	v_mfma_f32_16x16x32_bf16 v[20:23], v[140:143], v[180:183], v[18:21]
	v_mfma_f32_16x16x32_bf16 v[8:11], v[148:151], v[180:183], v[8:11]
	s_setprio 0
	s_barrier
	s_add_u32 s10, s10, 0x40080
	s_addc_u32 s11, s11, 0
	s_mov_b32 m0, s48
	v_lshl_add_u64 v[18:19], s[10:11], 0, v[196:197]
	global_load_lds_dwordx4 v[18:19], off
	v_lshl_add_u64 v[18:19], s[10:11], 0, v[192:193]
	s_mov_b32 m0, s49
	s_nop 0
	global_load_lds_dwordx4 v[18:19], off
	s_waitcnt vmcnt(6)
	s_barrier
	s_setprio 1
	v_mfma_f32_16x16x32_bf16 v[48:51], v[184:187], v[152:155], v[48:51]
	v_mfma_f32_16x16x32_bf16 v[60:63], v[200:203], v[152:155], v[60:63]
	v_mfma_f32_16x16x32_bf16 v[32:35], v[184:187], v[160:163], v[32:35]
	v_mfma_f32_16x16x32_bf16 v[40:43], v[200:203], v[160:163], v[40:43]
	v_mfma_f32_16x16x32_bf16 v[44:47], v[184:187], v[168:171], v[44:47]
	v_mfma_f32_16x16x32_bf16 v[24:27], v[200:203], v[168:171], v[24:27]
	v_mfma_f32_16x16x32_bf16 v[4:7], v[184:187], v[176:179], v[4:7]
	v_mfma_f32_16x16x32_bf16 v[0:3], v[200:203], v[176:179], v[0:3]
	v_mfma_f32_16x16x32_bf16 v[48:51], v[188:191], v[156:159], v[48:51]
	v_mfma_f32_16x16x32_bf16 v[60:63], v[204:207], v[156:159], v[60:63]
	v_mfma_f32_16x16x32_bf16 v[32:35], v[188:191], v[164:167], v[32:35]
	v_mfma_f32_16x16x32_bf16 v[40:43], v[204:207], v[164:167], v[40:43]
	v_mfma_f32_16x16x32_bf16 v[44:47], v[188:191], v[172:175], v[44:47]
	v_mfma_f32_16x16x32_bf16 v[24:27], v[204:207], v[172:175], v[24:27]
	v_mfma_f32_16x16x32_bf16 v[4:7], v[188:191], v[180:183], v[4:7]
	v_mfma_f32_16x16x32_bf16 v[0:3], v[204:207], v[180:183], v[0:3]
	s_setprio 0
	s_add_i32 s39, s39, 2
	s_add_u32 s8, s8, 0x100
	s_addc_u32 s9, s9, 0
	s_cmp_gt_u32 s39, 13
	s_barrier
	s_cbranch_scc0 .LBB0_979
	s_lshl_b32 s4, s28, 5
	s_lshl_b32 s5, s28, 10
	s_lshl_b32 s2, s34, 9
	v_readlane_b32 s3, v254, 31
	s_add_u32 s2, s3, s2
	v_readlane_b32 s3, v254, 32
	s_addc_u32 s3, s3, 0
	s_lshl_b32 s1, s1, 12
	s_or_b32 s5, s5, s1
	s_ashr_i32 s1, s0, 31
	s_lshl_b64 s[0:1], s[0:1], 17
	v_add_u32_e32 v12, s5, v208
	v_lshlrev_b32_e32 v13, 7, v209
	s_add_u32 s0, s12, s0
	v_lshl_add_u32 v12, v12, 3, v13
	s_addc_u32 s1, s13, s1
	v_ashrrev_i32_e32 v13, 31, v12
	v_lshl_add_u64 v[14:15], v[12:13], 1, s[0:1]
	global_load_dwordx4 v[16:19], v[14:15], off nt
	global_load_dwordx4 v[136:139], v[14:15], off offset:1024 nt
	global_load_dwordx4 v[140:143], v[14:15], off offset:2048 nt
	global_load_dwordx4 v[144:147], v[14:15], off offset:3072 nt
	s_movk_i32 s5, 0x1000
	s_add_i32 s17, s17, s78
	v_add_co_u32_e32 v160, vcc, s5, v14
	s_movk_i32 s6, 0x2000
	v_add_u32_e32 v148, s17, v208
	v_addc_co_u32_e32 v161, vcc, 0, v15, vcc
	v_ashrrev_i32_e32 v149, 31, v148
	v_add_co_u32_e32 v164, vcc, s6, v14
	v_lshlrev_b64 v[166:167], 11, v[148:149]
	s_nop 0
	v_addc_co_u32_e32 v165, vcc, 0, v15, vcc
	global_load_dwordx4 v[148:151], v[160:161], off offset:1024 nt
	global_load_dwordx4 v[152:155], v[160:161], off offset:2048 nt
	global_load_dwordx4 v[156:159], v[164:165], off offset:-4096 nt
	s_nop 0
	global_load_dwordx4 v[160:163], v[160:161], off offset:3072 nt
	global_load_dwordx4 v[180:183], v[164:165], off nt
	global_load_dwordx4 v[184:187], v[164:165], off offset:1024 nt
	global_load_dwordx4 v[188:191], v[164:165], off offset:2048 nt
	global_load_dwordx4 v[192:195], v[164:165], off offset:3072 nt
	v_add_co_u32_e32 v210, vcc, 0x3000, v14
	s_nop 1
	v_addc_co_u32_e32 v211, vcc, 0, v15, vcc
	global_load_dwordx4 v[196:199], v[210:211], off nt
	global_load_dwordx4 v[200:203], v[210:211], off offset:1024 nt
	global_load_dwordx4 v[204:207], v[210:211], off offset:2048 nt
	global_load_dwordx4 v[212:215], v[210:211], off offset:3072 nt
	v_lshl_add_u32 v12, v209, 3, s4
	v_ashrrev_i32_e32 v13, 31, v12
	v_lshl_add_u64 v[12:13], v[12:13], 1, s[2:3]
	v_lshl_add_u64 v[12:13], v[12:13], 0, v[166:167]
	s_mov_b64 s[0:1], 0x8000
	v_lshl_add_u64 v[166:167], v[12:13], 0, s[0:1]
	s_mov_b32 s0, 0x8000
	s_cmpk_lt_u32 s16, 0x100
	s_waitcnt vmcnt(0)
; __device__ __forceinline__ float bf_lo(unsigned w) { return __uint_as_float(w << 16); }
; __device__ __forceinline__ float bf_hi(unsigned w) { return __uint_as_float(w & 0xffff0000u); }
; __device__ __forceinline__ unsigned cvt_pk_bf16(float lo, float hi) { unsigned r; asm volatile("v_cvt_pk_bf16_f32 %0, %1, %2" : "=v"(r) : "v"(lo), "v"(hi)); return r; }
;     __device__ __forceinline__ void operator()(f32x4 (&acc)[2][2][4][2], const Unit& u, int wr, int wc, int fr, int fq) const {
;     ...
; #pragma unroll
;             for (int m = 0; m < 4; ++m) { const size_t row = (size_t)(row0 + ai * 128 + m * 16);
; #pragma unroll
;                 for (int bj = 0; bj < 2; ++bj) { const u32x4 g = g8[m][bj]; const f32x4 a0 = acc[ai][bj][m][0], a1 = acc[ai][bj][m][1];
;                     u32x4 w; w.x = cvt_pk_bf16(a0[0] * bf_lo(g.x), a0[1] * bf_hi(g.x)); w.y = cvt_pk_bf16(a0[2] * bf_lo(g.y), a0[3] * bf_hi(g.y));
;                     w.z = cvt_pk_bf16(a1[0] * bf_lo(g.z), a1[1] * bf_hi(g.z)); w.w = cvt_pk_bf16(a1[2] * bf_lo(g.w), a1[3] * bf_hi(g.w));
;                     *(u32x4*)(mg + row * 1024 + col0 + bj * 128) = w; } } }
	v_lshlrev_b32_e32 v168, 16, v16
	v_and_b32_e32 v16, 0xffff0000, v16
	v_lshlrev_b32_e32 v169, 16, v17
	v_and_b32_e32 v17, 0xffff0000, v17
	v_lshlrev_b32_e32 v170, 16, v18
	v_and_b32_e32 v18, 0xffff0000, v18
	v_lshlrev_b32_e32 v171, 16, v19
	v_and_b32_e32 v19, 0xffff0000, v19
	v_mul_f32_e32 v16, v105, v16
	v_mul_f32_e32 v17, v107, v17
	v_mul_f32_e32 v18, v109, v18
	v_lshlrev_b32_e32 v172, 16, v136
	v_and_b32_e32 v136, 0xffff0000, v136
	v_lshlrev_b32_e32 v173, 16, v137
	v_and_b32_e32 v137, 0xffff0000, v137
	v_lshlrev_b32_e32 v174, 16, v138
	v_and_b32_e32 v138, 0xffff0000, v138
	v_mul_f32_e32 v104, v104, v168
	v_mul_f32_e32 v105, v106, v169
	v_mul_f32_e32 v106, v108, v170
	v_mul_f32_e32 v19, v111, v19
	v_cvt_pk_bf16_f32 v16, v104, v16
	v_cvt_pk_bf16_f32 v17, v105, v17
	v_cvt_pk_bf16_f32 v18, v106, v18
	v_lshlrev_b32_e32 v175, 16, v139
	v_and_b32_e32 v139, 0xffff0000, v139
	v_mul_f32_e32 v107, v110, v171
	v_mul_f32_e32 v108, v112, v172
	v_mul_f32_e32 v109, v113, v136
	v_mul_f32_e32 v110, v114, v173
	v_mul_f32_e32 v111, v115, v137
	v_mul_f32_e32 v112, v120, v174
	v_mul_f32_e32 v113, v121, v138
	v_cvt_pk_bf16_f32 v19, v107, v19
	global_store_dwordx4 v[12:13], v[16:19], off
	v_mul_f32_e32 v114, v122, v175
	v_mul_f32_e32 v115, v123, v139
	v_cvt_pk_bf16_f32 v16, v108, v109
	v_cvt_pk_bf16_f32 v17, v110, v111
	v_cvt_pk_bf16_f32 v18, v112, v113
	v_cvt_pk_bf16_f32 v19, v114, v115
	global_store_dwordx4 v[12:13], v[16:19], off offset:256
	v_lshlrev_b32_e32 v176, 16, v140
	v_and_b32_e32 v140, 0xffff0000, v140
	v_lshlrev_b32_e32 v17, 16, v141
	v_and_b32_e32 v18, 0xffff0000, v141
	v_mul_f32_e32 v17, v126, v17
	v_mul_f32_e32 v18, v127, v18
	v_mul_f32_e32 v120, v124, v176
	v_mul_f32_e32 v121, v125, v140
	v_cvt_pk_bf16_f32 v16, v120, v121
	v_cvt_pk_bf16_f32 v17, v17, v18
	v_lshlrev_b32_e32 v18, 16, v142
	v_and_b32_e32 v19, 0xffff0000, v142
	v_mul_f32_e32 v18, v116, v18
	v_mul_f32_e32 v19, v117, v19
	v_cvt_pk_bf16_f32 v18, v18, v19
	v_lshlrev_b32_e32 v19, 16, v143
	v_and_b32_e32 v104, 0xffff0000, v143
	v_mul_f32_e32 v19, v118, v19
	v_mul_f32_e32 v104, v119, v104
	v_cvt_pk_bf16_f32 v19, v19, v104
	v_add_co_u32_e32 v104, vcc, s0, v12
	s_mov_b64 s[0:1], 0x10000
	s_nop 0
	v_addc_co_u32_e32 v105, vcc, 0, v13, vcc
	global_store_dwordx4 v[104:105], v[16:19], off
	s_nop 1
	v_lshlrev_b32_e32 v16, 16, v144
	v_and_b32_e32 v17, 0xffff0000, v144
	v_mul_f32_e32 v16, v100, v16
	v_mul_f32_e32 v17, v101, v17
	v_cvt_pk_bf16_f32 v16, v16, v17
	v_lshlrev_b32_e32 v17, 16, v145
	v_and_b32_e32 v18, 0xffff0000, v145
	v_mul_f32_e32 v17, v102, v17
	v_mul_f32_e32 v18, v103, v18
	v_cvt_pk_bf16_f32 v17, v17, v18
	v_lshlrev_b32_e32 v18, 16, v146
	v_and_b32_e32 v19, 0xffff0000, v146
	v_mul_f32_e32 v18, v92, v18
	v_mul_f32_e32 v19, v93, v19
	v_cvt_pk_bf16_f32 v18, v18, v19
	v_lshlrev_b32_e32 v19, 16, v147
	v_mul_f32_e32 v19, v94, v19
	v_and_b32_e32 v92, 0xffff0000, v147
	v_mul_f32_e32 v92, v95, v92
	v_cvt_pk_bf16_f32 v19, v19, v92
	global_store_dwordx4 v[166:167], v[16:19], off offset:256
	v_lshl_add_u64 v[92:93], v[12:13], 0, s[0:1]
	s_mov_b32 s0, 0x10000
	v_lshlrev_b32_e32 v16, 16, v156
	v_and_b32_e32 v17, 0xffff0000, v156
	v_mul_f32_e32 v16, v96, v16
	v_mul_f32_e32 v17, v97, v17
	v_cvt_pk_bf16_f32 v16, v16, v17
	v_lshlrev_b32_e32 v17, 16, v157
	v_and_b32_e32 v18, 0xffff0000, v157
	v_mul_f32_e32 v17, v98, v17
	v_mul_f32_e32 v18, v99, v18
	v_cvt_pk_bf16_f32 v17, v17, v18
	v_lshlrev_b32_e32 v18, 16, v158
	v_and_b32_e32 v19, 0xffff0000, v158
	v_mul_f32_e32 v18, v88, v18
	v_mul_f32_e32 v19, v89, v19
	v_cvt_pk_bf16_f32 v18, v18, v19
	v_lshlrev_b32_e32 v19, 16, v159
	v_and_b32_e32 v88, 0xffff0000, v159
	v_mul_f32_e32 v19, v90, v19
	v_mul_f32_e32 v88, v91, v88
	v_cvt_pk_bf16_f32 v19, v19, v88
	v_add_co_u32_e32 v88, vcc, s0, v12
	s_mov_b64 s[0:1], 0x18000
	s_nop 0
	v_addc_co_u32_e32 v89, vcc, 0, v13, vcc
	global_store_dwordx4 v[88:89], v[16:19], off
	s_nop 1
	v_lshlrev_b32_e32 v16, 16, v148
	v_and_b32_e32 v17, 0xffff0000, v148
	v_mul_f32_e32 v16, v84, v16
	v_mul_f32_e32 v17, v85, v17
	v_cvt_pk_bf16_f32 v16, v16, v17
	v_lshlrev_b32_e32 v17, 16, v149
	v_and_b32_e32 v18, 0xffff0000, v149
	v_mul_f32_e32 v17, v86, v17
	v_mul_f32_e32 v18, v87, v18
	v_cvt_pk_bf16_f32 v17, v17, v18
	v_lshlrev_b32_e32 v18, 16, v150
	v_and_b32_e32 v19, 0xffff0000, v150
	v_mul_f32_e32 v18, v76, v18
	v_mul_f32_e32 v19, v77, v19
	v_cvt_pk_bf16_f32 v18, v18, v19
	v_lshlrev_b32_e32 v19, 16, v151
	v_mul_f32_e32 v19, v78, v19
	v_and_b32_e32 v76, 0xffff0000, v151
	v_mul_f32_e32 v76, v79, v76
	v_cvt_pk_bf16_f32 v19, v19, v76
	global_store_dwordx4 v[92:93], v[16:19], off offset:256
	v_lshl_add_u64 v[76:77], v[12:13], 0, s[0:1]
	s_mov_b32 s0, 0x18000
	v_lshlrev_b32_e32 v16, 16, v152
	v_and_b32_e32 v17, 0xffff0000, v152
	v_mul_f32_e32 v16, v80, v16
	v_mul_f32_e32 v17, v81, v17
	v_cvt_pk_bf16_f32 v16, v16, v17
	v_lshlrev_b32_e32 v17, 16, v153
	v_and_b32_e32 v18, 0xffff0000, v153
	v_mul_f32_e32 v17, v82, v17
	v_mul_f32_e32 v18, v83, v18
	v_cvt_pk_bf16_f32 v17, v17, v18
	v_lshlrev_b32_e32 v18, 16, v154
	v_and_b32_e32 v19, 0xffff0000, v154
	v_mul_f32_e32 v18, v72, v18
	v_mul_f32_e32 v19, v73, v19
	v_cvt_pk_bf16_f32 v18, v18, v19
	v_lshlrev_b32_e32 v19, 16, v155
	v_and_b32_e32 v72, 0xffff0000, v155
	v_mul_f32_e32 v19, v74, v19
	v_mul_f32_e32 v72, v75, v72
	v_cvt_pk_bf16_f32 v19, v19, v72
	v_add_co_u32_e32 v72, vcc, s0, v12
	s_movk_i32 s0, 0x3000
	s_nop 0
	v_addc_co_u32_e32 v73, vcc, 0, v13, vcc
	global_store_dwordx4 v[72:73], v[16:19], off
	v_add_co_u32_e32 v14, vcc, s0, v14
	s_nop 0
	v_lshlrev_b32_e32 v16, 16, v160
	v_and_b32_e32 v17, 0xffff0000, v160
	v_mul_f32_e32 v16, v68, v16
	v_mul_f32_e32 v17, v69, v17
	v_cvt_pk_bf16_f32 v16, v16, v17
; __device__ __forceinline__ float bf_lo(unsigned w) { return __uint_as_float(w << 16); }
; __device__ __forceinline__ float bf_hi(unsigned w) { return __uint_as_float(w & 0xffff0000u); }
; __device__ __forceinline__ unsigned cvt_pk_bf16(float lo, float hi) { unsigned r; asm volatile("v_cvt_pk_bf16_f32 %0, %1, %2" : "=v"(r) : "v"(lo), "v"(hi)); return r; }
;     __device__ __forceinline__ void operator()(f32x4 (&acc)[2][2][4][2], const Unit& u, int wr, int wc, int fr, int fq) const {
;     ...
;         for (int ai = 0; ai < 2; ++ai) {
;             u32x4 g8[4][2];
; #pragma unroll
;             for (int m = 0; m < 4; ++m)
; #pragma unroll
;                 for (int bj = 0; bj < 2; ++bj) g8[m][bj] = __builtin_nontemporal_load((const u32x4*)(gb + ((ai * 4 + m) * 2 + bj) * 512));
; #pragma unroll
;             for (int m = 0; m < 4; ++m) { const size_t row = (size_t)(row0 + ai * 128 + m * 16);
; #pragma unroll
;                 for (int bj = 0; bj < 2; ++bj) { const u32x4 g = g8[m][bj]; const f32x4 a0 = acc[ai][bj][m][0], a1 = acc[ai][bj][m][1];
;                     u32x4 w; w.x = cvt_pk_bf16(a0[0] * bf_lo(g.x), a0[1] * bf_hi(g.x)); w.y = cvt_pk_bf16(a0[2] * bf_lo(g.y), a0[3] * bf_hi(g.y));
;                     w.z = cvt_pk_bf16(a1[0] * bf_lo(g.z), a1[1] * bf_hi(g.z)); w.w = cvt_pk_bf16(a1[2] * bf_lo(g.w), a1[3] * bf_hi(g.w));
;                     *(u32x4*)(mg + row * 1024 + col0 + bj * 128) = w; } } }
	v_lshlrev_b32_e32 v17, 16, v161
	v_and_b32_e32 v18, 0xffff0000, v161
	v_mul_f32_e32 v17, v70, v17
	v_mul_f32_e32 v18, v71, v18
	v_cvt_pk_bf16_f32 v17, v17, v18
	v_lshlrev_b32_e32 v18, 16, v162
	v_and_b32_e32 v19, 0xffff0000, v162
	v_mul_f32_e32 v18, v128, v18
	v_mul_f32_e32 v19, v129, v19
	v_cvt_pk_bf16_f32 v18, v18, v19
	v_lshlrev_b32_e32 v19, 16, v163
	v_mul_f32_e32 v19, v130, v19
	v_and_b32_e32 v68, 0xffff0000, v163
	v_mul_f32_e32 v68, v131, v68
	v_cvt_pk_bf16_f32 v19, v19, v68
	global_store_dwordx4 v[76:77], v[16:19], off offset:256
	v_mov_b32_e32 v68, v184
	v_mov_b32_e32 v69, v185
	v_mov_b32_e32 v70, v186
	v_mov_b32_e32 v71, v187
	v_mov_b32_e32 v72, v188
	v_mov_b32_e32 v73, v189
	v_mov_b32_e32 v74, v190
	v_mov_b32_e32 v75, v191
	v_mov_b32_e32 v80, v196
	v_mov_b32_e32 v81, v197
	v_mov_b32_e32 v82, v198
	v_mov_b32_e32 v83, v199
	v_mov_b32_e32 v84, v200
	v_mov_b32_e32 v85, v201
	v_mov_b32_e32 v86, v202
	v_mov_b32_e32 v87, v203
	v_addc_co_u32_e32 v15, vcc, 0, v15, vcc
	v_mov_b32_e32 v88, v204
	v_mov_b32_e32 v89, v205
	v_mov_b32_e32 v90, v206
	v_mov_b32_e32 v91, v207
	v_mov_b32_e32 v92, v212
	v_mov_b32_e32 v93, v213
	v_mov_b32_e32 v94, v214
	v_mov_b32_e32 v95, v215
	v_mov_b32_e32 v76, v192
	v_mov_b32_e32 v77, v193
	v_mov_b32_e32 v78, v194
	v_mov_b32_e32 v79, v195
	v_mov_b32_e32 v16, v180
	v_mov_b32_e32 v17, v181
	v_mov_b32_e32 v18, v182
	v_mov_b32_e32 v19, v183
	s_mov_b64 s[0:1], 0x40000
	v_lshl_add_u64 v[96:97], v[12:13], 0, s[0:1]
	s_mov_b32 s0, 0x40000
	v_lshlrev_b32_e32 v14, 16, v16
	v_and_b32_e32 v15, 0xffff0000, v16
	v_mul_f32_e32 v14, v52, v14
	v_mul_f32_e32 v15, v53, v15
	v_cvt_pk_bf16_f32 v14, v14, v15
	v_lshlrev_b32_e32 v15, 16, v17
	v_and_b32_e32 v16, 0xffff0000, v17
	v_mul_f32_e32 v15, v54, v15
	v_mul_f32_e32 v16, v55, v16
	v_cvt_pk_bf16_f32 v15, v15, v16
	v_lshlrev_b32_e32 v16, 16, v18
	v_and_b32_e32 v17, 0xffff0000, v18
	v_mul_f32_e32 v16, v56, v16
	v_mul_f32_e32 v17, v57, v17
	v_cvt_pk_bf16_f32 v16, v16, v17
	v_lshlrev_b32_e32 v17, 16, v19
	v_and_b32_e32 v18, 0xffff0000, v19
	v_mul_f32_e32 v17, v58, v17
	v_mul_f32_e32 v18, v59, v18
	v_cvt_pk_bf16_f32 v17, v17, v18
	v_add_co_u32_e32 v18, vcc, s0, v12
	s_mov_b64 s[0:1], 0x48000
	s_nop 0
	v_addc_co_u32_e32 v19, vcc, 0, v13, vcc
	global_store_dwordx4 v[18:19], v[14:17], off
	v_and_b32_e32 v18, 0xffff0000, v71
	v_mul_f32_e32 v18, v63, v18
	v_lshlrev_b32_e32 v14, 16, v68
	v_and_b32_e32 v15, 0xffff0000, v68
	v_mul_f32_e32 v14, v48, v14
	v_mul_f32_e32 v15, v49, v15
	v_cvt_pk_bf16_f32 v14, v14, v15
	v_lshlrev_b32_e32 v15, 16, v69
	v_and_b32_e32 v16, 0xffff0000, v69
	v_mul_f32_e32 v15, v50, v15
	v_mul_f32_e32 v16, v51, v16
	v_cvt_pk_bf16_f32 v15, v15, v16
	v_lshlrev_b32_e32 v16, 16, v70
	v_and_b32_e32 v17, 0xffff0000, v70
	v_mul_f32_e32 v16, v60, v16
	v_mul_f32_e32 v17, v61, v17
	v_cvt_pk_bf16_f32 v16, v16, v17
	v_lshlrev_b32_e32 v17, 16, v71
	v_mul_f32_e32 v17, v62, v17
	v_cvt_pk_bf16_f32 v17, v17, v18
	global_store_dwordx4 v[96:97], v[14:17], off offset:256
	v_lshl_add_u64 v[18:19], v[12:13], 0, s[0:1]
	s_mov_b32 s0, 0x48000
	v_lshlrev_b32_e32 v14, 16, v72
	v_and_b32_e32 v15, 0xffff0000, v72
	v_mul_f32_e32 v14, v36, v14
	v_mul_f32_e32 v15, v37, v15
	v_cvt_pk_bf16_f32 v14, v14, v15
	v_lshlrev_b32_e32 v15, 16, v73
	v_and_b32_e32 v16, 0xffff0000, v73
	v_mul_f32_e32 v15, v38, v15
	v_mul_f32_e32 v16, v39, v16
	v_cvt_pk_bf16_f32 v15, v15, v16
	v_lshlrev_b32_e32 v16, 16, v74
	v_and_b32_e32 v17, 0xffff0000, v74
	v_mul_f32_e32 v16, v64, v16
	v_mul_f32_e32 v17, v65, v17
	v_cvt_pk_bf16_f32 v16, v16, v17
	v_lshlrev_b32_e32 v17, 16, v75
	v_and_b32_e32 v36, 0xffff0000, v75
	v_mul_f32_e32 v17, v66, v17
	v_mul_f32_e32 v36, v67, v36
	v_cvt_pk_bf16_f32 v17, v17, v36
	v_add_co_u32_e32 v36, vcc, s0, v12
	s_mov_b64 s[0:1], 0x50000
	s_nop 0
	v_addc_co_u32_e32 v37, vcc, 0, v13, vcc
	global_store_dwordx4 v[36:37], v[14:17], off
; __device__ __forceinline__ float bf_lo(unsigned w) { return __uint_as_float(w << 16); }
; __device__ __forceinline__ float bf_hi(unsigned w) { return __uint_as_float(w & 0xffff0000u); }
; __device__ __forceinline__ unsigned cvt_pk_bf16(float lo, float hi) { unsigned r; asm volatile("v_cvt_pk_bf16_f32 %0, %1, %2" : "=v"(r) : "v"(lo), "v"(hi)); return r; }
; #define PG8_WAIT_V(n) asm volatile("s_waitcnt vmcnt(" #n ")" ::: "memory")
; template <class Epi, class Sched, bool ZERO>
; __device__ __forceinline__ void gemm_phase_acc(LAS unsigned char* lds, const Gemm g, const Sched& S, const Epi& E, f32x4 (&acc)[2][2][4][2]) {
;     ...
;     PG8_WAIT_V(0);
;     __device__ __forceinline__ void operator()(f32x4 (&acc)[2][2][4][2], const Unit& u, int wr, int wc, int fr, int fq) const {
;     ...
;             for (int m = 0; m < 4; ++m) { const size_t row = (size_t)(row0 + ai * 128 + m * 16);
; #pragma unroll
;                 for (int bj = 0; bj < 2; ++bj) { const u32x4 g = g8[m][bj]; const f32x4 a0 = acc[ai][bj][m][0], a1 = acc[ai][bj][m][1];
;                     u32x4 w; w.x = cvt_pk_bf16(a0[0] * bf_lo(g.x), a0[1] * bf_hi(g.x)); w.y = cvt_pk_bf16(a0[2] * bf_lo(g.y), a0[3] * bf_hi(g.y));
;                     w.z = cvt_pk_bf16(a1[0] * bf_lo(g.z), a1[1] * bf_hi(g.z)); w.w = cvt_pk_bf16(a1[2] * bf_lo(g.w), a1[3] * bf_hi(g.w));
;                     *(u32x4*)(mg + row * 1024 + col0 + bj * 128) = w; } } }
	s_nop 1
	v_lshlrev_b32_e32 v14, 16, v76
	v_and_b32_e32 v15, 0xffff0000, v76
	v_mul_f32_e32 v14, v32, v14
	v_mul_f32_e32 v15, v33, v15
	v_cvt_pk_bf16_f32 v14, v14, v15
	v_lshlrev_b32_e32 v15, 16, v77
	v_and_b32_e32 v16, 0xffff0000, v77
	v_mul_f32_e32 v15, v34, v15
	v_mul_f32_e32 v16, v35, v16
	v_cvt_pk_bf16_f32 v15, v15, v16
	v_lshlrev_b32_e32 v16, 16, v78
	v_and_b32_e32 v17, 0xffff0000, v78
	v_mul_f32_e32 v16, v40, v16
	v_mul_f32_e32 v17, v41, v17
	v_cvt_pk_bf16_f32 v16, v16, v17
	v_lshlrev_b32_e32 v17, 16, v79
	v_mul_f32_e32 v17, v42, v17
	v_and_b32_e32 v32, 0xffff0000, v79
	v_mul_f32_e32 v32, v43, v32
	v_cvt_pk_bf16_f32 v17, v17, v32
	global_store_dwordx4 v[18:19], v[14:17], off offset:256
	v_lshl_add_u64 v[18:19], v[12:13], 0, s[0:1]
	s_mov_b32 s0, 0x50000
	v_lshlrev_b32_e32 v14, 16, v80
	v_and_b32_e32 v15, 0xffff0000, v80
	v_mul_f32_e32 v14, v28, v14
	v_mul_f32_e32 v15, v29, v15
	v_cvt_pk_bf16_f32 v14, v14, v15
	v_lshlrev_b32_e32 v15, 16, v81
	v_and_b32_e32 v16, 0xffff0000, v81
	v_mul_f32_e32 v15, v30, v15
	v_mul_f32_e32 v16, v31, v16
	v_cvt_pk_bf16_f32 v15, v15, v16
	v_lshlrev_b32_e32 v16, 16, v82
	v_and_b32_e32 v17, 0xffff0000, v82
	v_mul_f32_e32 v16, v132, v16
	v_mul_f32_e32 v17, v133, v17
	v_cvt_pk_bf16_f32 v16, v16, v17
	v_lshlrev_b32_e32 v17, 16, v83
	v_and_b32_e32 v28, 0xffff0000, v83
	v_mul_f32_e32 v17, v134, v17
	v_mul_f32_e32 v28, v135, v28
	v_cvt_pk_bf16_f32 v17, v17, v28
	v_add_co_u32_e32 v28, vcc, s0, v12
	s_mov_b64 s[0:1], 0x58000
	s_nop 0
	v_addc_co_u32_e32 v29, vcc, 0, v13, vcc
	global_store_dwordx4 v[28:29], v[14:17], off
	s_nop 1
	v_lshlrev_b32_e32 v14, 16, v84
	v_and_b32_e32 v15, 0xffff0000, v84
	v_mul_f32_e32 v14, v44, v14
	v_mul_f32_e32 v15, v45, v15
	v_cvt_pk_bf16_f32 v14, v14, v15
	v_lshlrev_b32_e32 v15, 16, v85
	v_and_b32_e32 v16, 0xffff0000, v85
	v_mul_f32_e32 v15, v46, v15
	v_mul_f32_e32 v16, v47, v16
	v_cvt_pk_bf16_f32 v15, v15, v16
	v_lshlrev_b32_e32 v16, 16, v86
	v_and_b32_e32 v17, 0xffff0000, v86
	v_mul_f32_e32 v16, v24, v16
	v_mul_f32_e32 v17, v25, v17
	v_cvt_pk_bf16_f32 v16, v16, v17
	v_lshlrev_b32_e32 v17, 16, v87
	v_mul_f32_e32 v17, v26, v17
	v_and_b32_e32 v24, 0xffff0000, v87
	v_mul_f32_e32 v24, v27, v24
	v_cvt_pk_bf16_f32 v17, v17, v24
	global_store_dwordx4 v[18:19], v[14:17], off offset:256
	v_lshl_add_u64 v[18:19], v[12:13], 0, s[0:1]
	s_mov_b32 s0, 0x58000
	v_lshlrev_b32_e32 v14, 16, v88
	v_and_b32_e32 v15, 0xffff0000, v88
	v_mul_f32_e32 v14, v20, v14
	v_mul_f32_e32 v15, v21, v15
	v_cvt_pk_bf16_f32 v14, v14, v15
	v_lshlrev_b32_e32 v15, 16, v89
	v_and_b32_e32 v16, 0xffff0000, v89
	v_mul_f32_e32 v15, v22, v15
	v_mul_f32_e32 v16, v23, v16
	v_cvt_pk_bf16_f32 v15, v15, v16
	v_lshlrev_b32_e32 v16, 16, v90
	v_mul_f32_e32 v8, v8, v16
	v_and_b32_e32 v16, 0xffff0000, v90
	v_mul_f32_e32 v9, v9, v16
	v_cvt_pk_bf16_f32 v16, v8, v9
	v_lshlrev_b32_e32 v8, 16, v91
	v_mul_f32_e32 v8, v10, v8
	v_and_b32_e32 v9, 0xffff0000, v91
	v_mul_f32_e32 v9, v11, v9
	v_cvt_pk_bf16_f32 v17, v8, v9
	v_add_co_u32_e32 v8, vcc, s0, v12
	s_nop 1
	v_addc_co_u32_e32 v9, vcc, 0, v13, vcc
	global_store_dwordx4 v[8:9], v[14:17], off
	v_lshlrev_b32_e32 v8, 16, v92
	v_mul_f32_e32 v4, v4, v8
	v_and_b32_e32 v8, 0xffff0000, v92
	v_mul_f32_e32 v5, v5, v8
	v_cvt_pk_bf16_f32 v4, v4, v5
	v_lshlrev_b32_e32 v5, 16, v93
	v_mul_f32_e32 v5, v6, v5
	v_and_b32_e32 v6, 0xffff0000, v93
	v_mul_f32_e32 v6, v7, v6
	v_cvt_pk_bf16_f32 v5, v5, v6
	v_lshlrev_b32_e32 v6, 16, v94
	v_mul_f32_e32 v0, v0, v6
	v_and_b32_e32 v6, 0xffff0000, v94
	v_mul_f32_e32 v1, v1, v6
	v_cvt_pk_bf16_f32 v6, v0, v1
	v_lshlrev_b32_e32 v0, 16, v95
	v_and_b32_e32 v1, 0xffff0000, v95
	v_mul_f32_e32 v0, v2, v0
	v_mul_f32_e32 v1, v3, v1
	v_cvt_pk_bf16_f32 v7, v0, v1
	global_store_dwordx4 v[18:19], v[4:7], off offset:256
	s_waitcnt vmcnt(0)
	s_cbranch_scc0 .LBB0_982
	s_barrier

;     __device__ __forceinline__ void fused(f32x4 (&acc)[2][2][4][2], const Unit& u, int wr, int wc, int fr, int fq, LAS unsigned char* lds) const {
;     ...
;         if (wid == 0) {
;             unsigned spins = 0;
;             while ((unsigned)__builtin_amdgcn_readfirstlane(__hip_atomic_load(cnt, __ATOMIC_RELAXED, __HIP_MEMORY_SCOPE_AGENT)) < 32u) { __builtin_amdgcn_s_sleep(2); if (++spins > (1u << 20)) break; }
;     ...
;         f32x4 fw[2][2];
; #pragma unroll
;         for (int bj = 0; bj < 2; ++bj)
; #pragma unroll
;             for (int n = 0; n < 2; ++n) fw[bj][n] = *(const f32x4*)(fnw + u.pn * 256 + col0 + bj * 128 + 4 * n);
.LBB0_1059:
	s_or_b64 exec, exec, s[6:7]
	v_readlane_b32 s20, v254, 20
	v_readlane_b32 s21, v254, 21
	s_add_u32 s20, s20, s2
	s_addc_u32 s21, s21, 0
	global_load_dwordx4 v[228:231], v192, s[20:21]
	global_load_dwordx4 v[232:235], v192, s[20:21] offset:16
	global_load_dwordx4 v[236:239], v192, s[20:21] offset:512
	global_load_dwordx4 v[240:243], v192, s[20:21] offset:528
	s_lshl_b32 s3, s12, 2
	s_or_b32 s3, s3, s13
	s_cmp_lg_u32 s3, 0
	s_cbranch_scc1 .LBB0_1065
	s_mov_b32 s8, 0x100001
	s_waitcnt lgkmcnt(0)
	v_mov_b32_e32 v1, 0
	s_branch .LBB0_1062

;     __device__ __forceinline__ void fused(f32x4 (&acc)[2][2][4][2], const Unit& u, int wr, int wc, int fr, int fq, LAS unsigned char* lds) const {
;     ...
;         f32x4 fw[2][2];
; #pragma unroll
;         for (int bj = 0; bj < 2; ++bj)
; #pragma unroll
;             for (int n = 0; n < 2; ++n) fw[bj][n] = *(const f32x4*)(fnw + u.pn * 256 + col0 + bj * 128 + 4 * n);
; #pragma unroll
;         for (int ai = 0; ai < 2; ++ai)
; #pragma unroll
;             for (int m = 0; m < 4; ++m) { const int rl = wr * 64 + fr + ai * 128 + m * 16; const float r = rs[rl]; float* op = out + (size_t)(u.pm * 256 + rl) * 1024 + u.pn * 256 + col0;
; #pragma unroll
;                 for (int bj = 0; bj < 2; ++bj)
; #pragma unroll
;                     for (int n = 0; n < 2; ++n) *(f32x4*)(op + bj * 128 + 4 * n) = acc[ai][bj][m][n] * r * fw[bj][n]; }
.LBB0_1067:
	s_or_b64 exec, exec, s[0:1]
	v_readlane_b32 s4, v254, 6
	v_readlane_b32 s14, v254, 16
	v_readlane_b32 s15, v254, 17
	v_readlane_b32 s18, v254, 20
	v_readlane_b32 s19, v254, 21
	s_mov_b64 s[14:15], s[18:19]
	s_add_u32 s0, s14, s2
	s_addc_u32 s1, s15, 0
	s_waitcnt lgkmcnt(0)
	s_barrier
	s_waitcnt vmcnt(0)
	v_mov_b32_e32 v12, v228
	v_mov_b32_e32 v13, v229
	v_mov_b32_e32 v14, v230
	v_mov_b32_e32 v15, v231
	v_mov_b32_e32 v8, v232
	v_mov_b32_e32 v9, v233
	v_mov_b32_e32 v10, v234
	v_mov_b32_e32 v11, v235
	v_mov_b32_e32 v4, v236
	v_mov_b32_e32 v5, v237
	v_mov_b32_e32 v6, v238
	v_mov_b32_e32 v7, v239
	v_mov_b32_e32 v0, v240
	v_mov_b32_e32 v1, v241
	v_mov_b32_e32 v2, v242
	v_mov_b32_e32 v3, v243
	v_lshl_add_u32 v138, v227, 2, 0
	v_add_u32_e32 v80, s78, v227
	ds_read2_b32 v[82:83], v138 offset1:16
	v_ashrrev_i32_e32 v81, 31, v80
	v_add_u32_e32 v84, 16, v80
	ds_read2_b32 v[122:123], v138 offset0:32 offset1:48
	v_add_u32_e32 v86, 32, v80
	v_lshlrev_b64 v[88:89], 12, v[80:81]
	v_ashrrev_i32_e32 v85, 31, v84
	s_mov_b32 s3, 0
	v_ashrrev_i32_e32 v87, 31, v86
	v_lshl_add_u64 v[88:89], s[68:69], 0, v[88:89]
	v_lshlrev_b64 v[84:85], 12, v[84:85]
	v_mov_b32_e32 v193, 0
	v_lshlrev_b64 v[86:87], 12, v[86:87]
	v_lshl_add_u64 v[88:89], v[88:89], 0, s[2:3]
	v_lshl_add_u64 v[84:85], s[68:69], 0, v[84:85]
	v_lshl_add_u64 v[86:87], s[68:69], 0, v[86:87]
	v_lshl_add_u64 v[124:125], v[88:89], 0, v[192:193]
	v_lshl_add_u64 v[84:85], v[84:85], 0, s[2:3]
	s_waitcnt lgkmcnt(1)
	v_pk_mul_f32 v[88:89], v[196:197], v[82:83] op_sel_hi:[1,0]
	v_pk_mul_f32 v[90:91], v[194:195], v[82:83] op_sel_hi:[1,0]
	v_pk_mul_f32 v[92:93], v[200:201], v[82:83] op_sel_hi:[1,0]
	v_pk_mul_f32 v[94:95], v[198:199], v[82:83] op_sel_hi:[1,0]
	v_pk_mul_f32 v[96:97], v[204:205], v[82:83] op_sel_hi:[1,0]
	v_pk_mul_f32 v[98:99], v[202:203], v[82:83] op_sel_hi:[1,0]
	v_pk_mul_f32 v[100:101], v[208:209], v[82:83] op_sel_hi:[1,0]
	v_pk_mul_f32 v[102:103], v[206:207], v[82:83] op_sel_hi:[1,0]
	v_mov_b32_e32 v82, v83
	v_lshl_add_u64 v[86:87], v[86:87], 0, s[2:3]
	v_lshl_add_u64 v[126:127], v[84:85], 0, v[192:193]
	s_waitcnt lgkmcnt(0)
	v_pk_mul_f32 v[114:115], v[172:173], v[122:123] op_sel_hi:[1,0]
	v_pk_mul_f32 v[116:117], v[174:175], v[122:123] op_sel_hi:[1,0]
	v_pk_mul_f32 v[118:119], v[168:169], v[122:123] op_sel_hi:[1,0]
	v_pk_mul_f32 v[120:121], v[170:171], v[122:123] op_sel_hi:[1,0]
	v_pk_mul_f32 v[104:105], v[188:189], v[82:83] op_sel_hi:[1,0]
	v_pk_mul_f32 v[106:107], v[190:191], v[82:83] op_sel_hi:[1,0]
	v_pk_mul_f32 v[108:109], v[184:185], v[82:83] op_sel_hi:[1,0]
	v_pk_mul_f32 v[110:111], v[186:187], v[82:83] op_sel_hi:[1,0]
	v_pk_mul_f32 v[112:113], v[180:181], v[82:83] op_sel_hi:[1,0]
	v_pk_mul_f32 v[132:133], v[182:183], v[82:83] op_sel_hi:[1,0]
	v_pk_mul_f32 v[134:135], v[176:177], v[82:83] op_sel_hi:[1,0]
	v_pk_mul_f32 v[136:137], v[178:179], v[82:83] op_sel_hi:[1,0]
	v_lshl_add_u64 v[128:129], v[86:87], 0, v[192:193]
	v_pk_mul_f32 v[130:131], v[164:165], v[122:123] op_sel_hi:[1,0]
	v_readlane_b32 s5, v254, 7
	v_readlane_b32 s6, v254, 8
	v_readlane_b32 s7, v254, 9
	v_readlane_b32 s8, v254, 10
	v_readlane_b32 s9, v254, 11
	v_readlane_b32 s10, v254, 12
	v_readlane_b32 s11, v254, 13
	v_readlane_b32 s12, v254, 14
	v_readlane_b32 s13, v254, 15
	v_readlane_b32 s16, v254, 18
	v_readlane_b32 s17, v254, 19
	s_waitcnt vmcnt(3)
	v_pk_mul_f32 v[84:85], v[14:15], v[90:91]
	v_pk_mul_f32 v[82:83], v[12:13], v[88:89]
	s_waitcnt vmcnt(2)
	v_pk_mul_f32 v[88:89], v[10:11], v[94:95]
	v_pk_mul_f32 v[86:87], v[8:9], v[92:93]
	s_waitcnt vmcnt(1)
	v_pk_mul_f32 v[92:93], v[6:7], v[98:99]
	v_pk_mul_f32 v[90:91], v[4:5], v[96:97]
	s_waitcnt vmcnt(0)
	v_pk_mul_f32 v[96:97], v[2:3], v[102:103]
	v_pk_mul_f32 v[94:95], v[0:1], v[100:101]
	v_pk_mul_f32 v[100:101], v[14:15], v[106:107]
	v_pk_mul_f32 v[98:99], v[12:13], v[104:105]
	v_pk_mul_f32 v[104:105], v[10:11], v[110:111]
	v_pk_mul_f32 v[102:103], v[8:9], v[108:109]
	v_pk_mul_f32 v[108:109], v[6:7], v[132:133]
	v_pk_mul_f32 v[106:107], v[4:5], v[112:113]
	v_pk_mul_f32 v[112:113], v[2:3], v[136:137]
	v_pk_mul_f32 v[110:111], v[0:1], v[134:135]
	v_pk_mul_f32 v[116:117], v[14:15], v[116:117]
	v_pk_mul_f32 v[114:115], v[12:13], v[114:115]
	v_pk_mul_f32 v[120:121], v[10:11], v[120:121]
	v_pk_mul_f32 v[118:119], v[8:9], v[118:119]
	global_store_dwordx4 v[124:125], v[82:85], off
	global_store_dwordx4 v[124:125], v[86:89], off offset:16
	global_store_dwordx4 v[124:125], v[90:93], off offset:512
	global_store_dwordx4 v[124:125], v[94:97], off offset:528
	global_store_dwordx4 v[126:127], v[98:101], off
	global_store_dwordx4 v[126:127], v[102:105], off offset:16
	global_store_dwordx4 v[126:127], v[106:109], off offset:512
	global_store_dwordx4 v[126:127], v[110:113], off offset:528
	global_store_dwordx4 v[128:129], v[114:117], off
	global_store_dwordx4 v[128:129], v[118:121], off offset:16
	v_pk_mul_f32 v[82:83], v[166:167], v[122:123] op_sel_hi:[1,0]
	v_mov_b32_e32 v88, v123
	v_pk_mul_f32 v[84:85], v[6:7], v[82:83]
	v_pk_mul_f32 v[82:83], v[4:5], v[130:131]
	global_store_dwordx4 v[128:129], v[82:85], off offset:512
	s_nop 1
	v_pk_mul_f32 v[82:83], v[160:161], v[122:123] op_sel_hi:[1,0]
	v_pk_mul_f32 v[84:85], v[162:163], v[122:123] op_sel_hi:[1,0]
	v_pk_mul_f32 v[82:83], v[0:1], v[82:83]
	v_pk_mul_f32 v[84:85], v[2:3], v[84:85]
	global_store_dwordx4 v[128:129], v[82:85], off offset:528
	s_nop 1
	v_add_u32_e32 v82, 48, v80
	v_ashrrev_i32_e32 v83, 31, v82
	v_lshlrev_b64 v[82:83], 12, v[82:83]
	v_lshl_add_u64 v[82:83], s[68:69], 0, v[82:83]
	v_lshl_add_u64 v[82:83], v[82:83], 0, s[2:3]
	v_lshl_add_u64 v[86:87], v[82:83], 0, v[192:193]
	v_pk_mul_f32 v[82:83], v[156:157], v[88:89] op_sel_hi:[1,0]
	v_pk_mul_f32 v[84:85], v[158:159], v[88:89] op_sel_hi:[1,0]
	v_pk_mul_f32 v[82:83], v[12:13], v[82:83]
	v_pk_mul_f32 v[84:85], v[14:15], v[84:85]
	global_store_dwordx4 v[86:87], v[82:85], off
	s_nop 1
	v_pk_mul_f32 v[82:83], v[152:153], v[88:89] op_sel_hi:[1,0]
	v_pk_mul_f32 v[84:85], v[154:155], v[88:89] op_sel_hi:[1,0]
	v_pk_mul_f32 v[82:83], v[8:9], v[82:83]
	v_pk_mul_f32 v[84:85], v[10:11], v[84:85]
	global_store_dwordx4 v[86:87], v[82:85], off offset:16
	s_nop 1
	v_pk_mul_f32 v[82:83], v[148:149], v[88:89] op_sel_hi:[1,0]
	v_pk_mul_f32 v[84:85], v[150:151], v[88:89] op_sel_hi:[1,0]
	v_pk_mul_f32 v[82:83], v[4:5], v[82:83]
	v_pk_mul_f32 v[84:85], v[6:7], v[84:85]
	global_store_dwordx4 v[86:87], v[82:85], off offset:512
	s_nop 1
	v_pk_mul_f32 v[82:83], v[144:145], v[88:89] op_sel_hi:[1,0]
	v_pk_mul_f32 v[84:85], v[146:147], v[88:89] op_sel_hi:[1,0]
	v_pk_mul_f32 v[82:83], v[0:1], v[82:83]
	v_pk_mul_f32 v[84:85], v[2:3], v[84:85]
	global_store_dwordx4 v[86:87], v[82:85], off offset:528
	ds_read2_b32 v[82:83], v138 offset0:128 offset1:144
	s_waitcnt lgkmcnt(0)
;     __device__ __forceinline__ void fused(f32x4 (&acc)[2][2][4][2], const Unit& u, int wr, int wc, int fr, int fq, LAS unsigned char* lds) const {
;     ...
; #pragma unroll
;         for (int ai = 0; ai < 2; ++ai)
; #pragma unroll
;             for (int m = 0; m < 4; ++m) { const int rl = wr * 64 + fr + ai * 128 + m * 16; const float r = rs[rl]; float* op = out + (size_t)(u.pm * 256 + rl) * 1024 + u.pn * 256 + col0;
; #pragma unroll
;                 for (int bj = 0; bj < 2; ++bj)
; #pragma unroll
;                     for (int n = 0; n < 2; ++n) *(f32x4*)(op + bj * 128 + 4 * n) = acc[ai][bj][m][n] * r * fw[bj][n]; }
	v_pk_mul_f32 v[48:49], v[48:49], v[82:83] op_sel_hi:[1,0]
	v_add_u32_e32 v84, 0x80, v80
	v_ashrrev_i32_e32 v85, 31, v84
	v_lshlrev_b64 v[84:85], 12, v[84:85]
	v_lshl_add_u64 v[84:85], s[68:69], 0, v[84:85]
	v_lshl_add_u64 v[84:85], v[84:85], 0, s[2:3]
	v_pk_mul_f32 v[50:51], v[50:51], v[82:83] op_sel_hi:[1,0]
	v_lshl_add_u64 v[84:85], v[84:85], 0, v[192:193]
	v_pk_mul_f32 v[50:51], v[2:3], v[50:51]
	v_pk_mul_f32 v[48:49], v[0:1], v[48:49]
	global_store_dwordx4 v[84:85], v[48:51], off offset:528
	v_pk_mul_f32 v[60:61], v[60:61], v[82:83] op_sel_hi:[1,0]
	v_pk_mul_f32 v[62:63], v[62:63], v[82:83] op_sel_hi:[1,0]
	v_add_u32_e32 v48, 0x90, v80
	v_ashrrev_i32_e32 v49, 31, v48
	v_lshlrev_b64 v[48:49], 12, v[48:49]
	v_lshl_add_u64 v[48:49], s[68:69], 0, v[48:49]
	v_mov_b32_e32 v50, v83
	v_lshl_add_u64 v[48:49], v[48:49], 0, s[2:3]
	v_pk_mul_f32 v[32:33], v[32:33], v[50:51] op_sel_hi:[1,0]
	v_pk_mul_f32 v[34:35], v[34:35], v[50:51] op_sel_hi:[1,0]
	v_lshl_add_u64 v[48:49], v[48:49], 0, v[192:193]
	v_pk_mul_f32 v[34:35], v[2:3], v[34:35]
	v_pk_mul_f32 v[32:33], v[0:1], v[32:33]
	global_store_dwordx4 v[48:49], v[32:35], off offset:528
	ds_read2_b32 v[32:33], v138 offset0:160 offset1:176
	v_pk_mul_f32 v[44:45], v[44:45], v[50:51] op_sel_hi:[1,0]
	v_add_u32_e32 v34, 0xa0, v80
	v_ashrrev_i32_e32 v35, 31, v34
	v_lshlrev_b64 v[34:35], 12, v[34:35]
	v_lshl_add_u64 v[34:35], s[68:69], 0, v[34:35]
	v_lshl_add_u64 v[34:35], v[34:35], 0, s[2:3]
	s_waitcnt lgkmcnt(0)
	v_pk_mul_f32 v[16:17], v[16:17], v[32:33] op_sel_hi:[1,0]
	v_pk_mul_f32 v[18:19], v[18:19], v[32:33] op_sel_hi:[1,0]
	v_lshl_add_u64 v[34:35], v[34:35], 0, v[192:193]
	v_pk_mul_f32 v[18:19], v[2:3], v[18:19]
	v_pk_mul_f32 v[16:17], v[0:1], v[16:17]
	global_store_dwordx4 v[34:35], v[16:19], off offset:528
	v_pk_mul_f32 v[20:21], v[20:21], v[32:33] op_sel_hi:[1,0]
	v_pk_mul_f32 v[22:23], v[22:23], v[32:33] op_sel_hi:[1,0]
	v_add_u32_e32 v16, 0xb0, v80
	v_ashrrev_i32_e32 v17, 31, v16
	v_lshlrev_b64 v[16:17], 12, v[16:17]
	v_pk_mul_f32 v[22:23], v[6:7], v[22:23]
	v_pk_mul_f32 v[20:21], v[4:5], v[20:21]
	v_lshl_add_u64 v[16:17], s[68:69], 0, v[16:17]
	v_mov_b32_e32 v18, v33
	v_pk_mul_f32 v[46:47], v[46:47], v[50:51] op_sel_hi:[1,0]
	v_pk_mul_f32 v[28:29], v[28:29], v[32:33] op_sel_hi:[1,0]
	v_pk_mul_f32 v[30:31], v[30:31], v[32:33] op_sel_hi:[1,0]
	global_store_dwordx4 v[34:35], v[20:23], off offset:512
	v_lshl_add_u64 v[16:17], v[16:17], 0, s[2:3]
	v_pk_mul_f32 v[62:63], v[14:15], v[62:63]
	v_pk_mul_f32 v[20:21], v[76:77], v[18:19] op_sel_hi:[1,0]
	v_pk_mul_f32 v[22:23], v[78:79], v[18:19] op_sel_hi:[1,0]
	v_pk_mul_f32 v[60:61], v[12:13], v[60:61]
	v_pk_mul_f32 v[46:47], v[14:15], v[46:47]
	v_pk_mul_f32 v[44:45], v[12:13], v[44:45]
	v_pk_mul_f32 v[30:31], v[14:15], v[30:31]
	v_pk_mul_f32 v[28:29], v[12:13], v[28:29]
	v_lshl_add_u64 v[16:17], v[16:17], 0, v[192:193]
	v_pk_mul_f32 v[14:15], v[14:15], v[22:23]
	v_pk_mul_f32 v[12:13], v[12:13], v[20:21]
	v_pk_mul_f32 v[56:57], v[56:57], v[82:83] op_sel_hi:[1,0]
	v_pk_mul_f32 v[58:59], v[58:59], v[82:83] op_sel_hi:[1,0]
	v_pk_mul_f32 v[40:41], v[40:41], v[50:51] op_sel_hi:[1,0]
	v_pk_mul_f32 v[42:43], v[42:43], v[50:51] op_sel_hi:[1,0]
	v_pk_mul_f32 v[24:25], v[24:25], v[32:33] op_sel_hi:[1,0]
	v_pk_mul_f32 v[26:27], v[26:27], v[32:33] op_sel_hi:[1,0]
	global_store_dwordx4 v[16:17], v[12:15], off
	v_pk_mul_f32 v[58:59], v[10:11], v[58:59]
	v_pk_mul_f32 v[56:57], v[8:9], v[56:57]
	v_pk_mul_f32 v[12:13], v[72:73], v[18:19] op_sel_hi:[1,0]
	v_pk_mul_f32 v[14:15], v[74:75], v[18:19] op_sel_hi:[1,0]
	v_pk_mul_f32 v[42:43], v[10:11], v[42:43]
	v_pk_mul_f32 v[40:41], v[8:9], v[40:41]
	v_pk_mul_f32 v[26:27], v[10:11], v[26:27]
	v_pk_mul_f32 v[24:25], v[8:9], v[24:25]
	v_pk_mul_f32 v[10:11], v[10:11], v[14:15]
	v_pk_mul_f32 v[8:9], v[8:9], v[12:13]
	v_pk_mul_f32 v[52:53], v[52:53], v[82:83] op_sel_hi:[1,0]
	v_pk_mul_f32 v[54:55], v[54:55], v[82:83] op_sel_hi:[1,0]
	v_pk_mul_f32 v[36:37], v[36:37], v[50:51] op_sel_hi:[1,0]
	v_pk_mul_f32 v[38:39], v[38:39], v[50:51] op_sel_hi:[1,0]
	global_store_dwordx4 v[16:17], v[8:11], off offset:16
	v_pk_mul_f32 v[54:55], v[6:7], v[54:55]
	v_pk_mul_f32 v[52:53], v[4:5], v[52:53]
	v_pk_mul_f32 v[8:9], v[68:69], v[18:19] op_sel_hi:[1,0]
	v_pk_mul_f32 v[10:11], v[70:71], v[18:19] op_sel_hi:[1,0]
	v_pk_mul_f32 v[38:39], v[6:7], v[38:39]
	v_pk_mul_f32 v[36:37], v[4:5], v[36:37]
	v_pk_mul_f32 v[6:7], v[6:7], v[10:11]
	v_pk_mul_f32 v[4:5], v[4:5], v[8:9]
	global_store_dwordx4 v[16:17], v[4:7], off offset:512
	global_store_dwordx4 v[84:85], v[60:63], off
	global_store_dwordx4 v[84:85], v[56:59], off offset:16
	v_pk_mul_f32 v[4:5], v[64:65], v[18:19] op_sel_hi:[1,0]
	v_pk_mul_f32 v[6:7], v[66:67], v[18:19] op_sel_hi:[1,0]
	v_pk_mul_f32 v[0:1], v[0:1], v[4:5]
	v_pk_mul_f32 v[2:3], v[2:3], v[6:7]
	global_store_dwordx4 v[84:85], v[52:55], off offset:512
	global_store_dwordx4 v[48:49], v[44:47], off
	global_store_dwordx4 v[48:49], v[40:43], off offset:16
	global_store_dwordx4 v[48:49], v[36:39], off offset:512
	global_store_dwordx4 v[34:35], v[28:31], off
	global_store_dwordx4 v[34:35], v[24:27], off offset:16
	global_store_dwordx4 v[16:17], v[0:3], off offset:528
	s_endpgm
